# phase 3 out-projection prompt tiles moved onto the 8-phase 256x256 LDS-DMA tile engine (K=2048, one tile per WG, per-range rstd folded into the single accumulator set in Horner form, f32 tile + residu
# speedup vs baseline: 1.0309x; 1.0285x over previous
;     ...
;     if (NH > 0) {
;       for (int idx = tid; idx < BM * NH; idx += NTHR) {
;         int row = idx / NH, h = idx % NH;
;         const float* pp = parts + (size_t)(m0 + row) * 64 + h * (64 / NH);
; template <int EPI>
; __device__ void gemm8_phase(const Params& p, const u16* __restrict__ A, const u16* __restrict__ Bt, const int K, const int nN,
;                             unsigned char* smem, const int rep) {
;     ...
;   const int nM = T_TOK / BM8, nwg = nM * nN;
;   const int wid = (int)p.wv, lane = (int)p.tidx & 63, wr = wid >> 2, wc = wid & 3, fr = lane & 15, fq = lane >> 4;
;   const int nt = K / BK8;
;   const __amdgpu_buffer_rsrc_t rsrc_A = __builtin_amdgcn_make_buffer_rsrc((void*)A, (short)0, T_TOK * K * 2, 0x00020000);
;   const __amdgpu_buffer_rsrc_t rsrc_Bt = __builtin_amdgcn_make_buffer_rsrc((void*)Bt, (short)0, nN * 256 * K * 2, 0x00020000);
;   int voff0, voff1;
;   {
;     int r_, c_;
;     stage_rc((int)p.tidx * 16, r_, c_);
;     voff0 = (r_ * K + c_) * 2;
;     stage_rc((int)p.tidx * 16 + 8192, r_, c_);
;     voff1 = (r_ * K + c_) * 2;
;   }
.LBB0_700:
	s_cmp_lt_i32 s86, 4
	s_cselect_b64 s[0:1], -1, 0
	s_cmp_gt_i32 s88, 2
	s_cselect_b64 s[2:3], -1, 0
	s_and_b64 s[0:1], s[0:1], s[2:3]
	s_andn2_b64 vcc, exec, s[0:1]
	s_cbranch_vccnz .LBB0_891
	s_mov_b32 s8, s84
	s_mov_b32 s22, s85
	v_mbcnt_lo_u32_b32 v0, -1, 0
	v_readlane_b32 s2, v255, 6
	v_mbcnt_hi_u32_b32 v195, -1, v0
	s_nop 0
	v_lshl_add_u32 v252, s2, 6, v195
	v_bfe_i32 v1, v252, 27, 1
	v_lshlrev_b32_e32 v138, 4, v252
	v_lshrrev_b32_e32 v1, 22, v1
	v_add_u32_e32 v1, v138, v1
	v_and_b32_e32 v1, 0xfffffc00, v1
	v_sub_u32_e32 v1, v138, v1
	v_lshrrev_b32_e32 v2, 4, v1
	v_bitop3_b32 v1, v2, v1, 32 bitop3:0x6c
	v_ashrrev_i32_e32 v0, 31, v252
	v_ashrrev_i32_e32 v3, 31, v1
	v_lshrrev_b32_e32 v0, 26, v0
	v_lshrrev_b32_e32 v3, 26, v3
	v_add_u32_e32 v0, v252, v0
	v_add_u32_e32 v3, v1, v3
	v_ashrrev_i32_e32 v0, 6, v0
	v_lshrrev_b32_e32 v4, 6, v3
	v_and_b32_e32 v3, 0xc0, v3
	v_lshlrev_b32_e32 v2, 3, v0
	v_lshlrev_b32_e32 v0, 5, v0
	v_sub_u32_e32 v1, v1, v3
	v_mov_b32_e32 v3, 1
	v_and_b32_e32 v2, 0x1ffff0, v2
	v_and_b32_e32 v0, 32, v0
	v_ashrrev_i16_sdwa v1, v3, sext(v1) dst_sel:DWORD dst_unused:UNUSED_PAD src0_sel:DWORD src1_sel:BYTE_0
	v_add_u32_sdwa v0, v0, sext(v1) dst_sel:DWORD dst_unused:UNUSED_PAD src0_sel:DWORD src1_sel:WORD_0
	v_add_lshl_u32 v1, v4, v2, 12
	v_add_u32_e32 v140, 0x2000, v138
	v_lshl_add_u32 v139, v0, 1, v1
	v_ashrrev_i32_e32 v0, 31, v140
	v_lshrrev_b32_e32 v0, 22, v0
	v_add_u32_e32 v0, v140, v0
	v_ashrrev_i32_e32 v0, 10, v0
	v_mul_i32_i24_e32 v1, 0x400, v0
	v_sub_u32_e32 v1, v140, v1
	v_lshrrev_b32_e32 v2, 4, v1
	v_bitop3_b32 v1, v2, v1, 32 bitop3:0x6c
	v_ashrrev_i32_e32 v4, 31, v1
	v_lshrrev_b32_e32 v4, 26, v4
	v_add_u32_e32 v4, v1, v4
	v_lshrrev_b32_e32 v5, 6, v4
	v_and_b32_e32 v4, 0xc0, v4
	v_lshlrev_b32_e32 v2, 3, v0
	v_lshlrev_b32_e32 v0, 5, v0
	v_sub_u32_e32 v1, v1, v4
	s_add_u32 s12, s8, 0x2242000
	v_and_b32_e32 v2, 0x1ffff0, v2
	v_and_b32_e32 v0, 32, v0
	v_ashrrev_i16_sdwa v1, v3, sext(v1) dst_sel:DWORD dst_unused:UNUSED_PAD src0_sel:DWORD src1_sel:BYTE_0
	s_addc_u32 s0, s22, 0
	v_add_u32_sdwa v0, v0, sext(v1) dst_sel:DWORD dst_unused:UNUSED_PAD src0_sel:DWORD src1_sel:WORD_0
	v_add_lshl_u32 v1, v5, v2, 12
	s_and_b32 s13, s0, 0xffff
	s_and_b32 s9, s22, 0xffff
	v_lshl_add_u32 v141, v0, 1, v1
	v_and_b32_e32 v0, 15, v195
	v_bfe_u32 v1, v252, 4, 2
	s_and_b32 s3, s2, 3
	s_ashr_i32 s4, s2, 2
	s_cmp_eq_u32 s4, 1
	v_lshlrev_b32_e32 v2, 4, v1
	v_lshlrev_b32_e32 v3, 6, v0
	v_lshlrev_b32_e32 v5, 2, v195
	s_cselect_b64 s[0:1], -1, 0
	s_lshl_b32 s5, s3, 12
	v_or_b32_e32 v4, v2, v3
	v_and_b32_e32 v5, 32, v5
	s_mov_b32 s6, 0x10000
	v_bitop3_b32 v6, v4, s6, v5 bitop3:0xde
	s_mov_b32 s6, 0x14000
	s_cmp_lt_u32 s2, 4
	v_bitop3_b32 v7, v4, s6, v5 bitop3:0xde
	s_mov_b32 s6, 0x18000
	s_cselect_b64 s[16:17], -1, 0
	s_lshl_b32 s24, s3, 5
	v_bitop3_b32 v8, v4, s6, v5 bitop3:0xde
	s_mov_b32 s6, 0x1c000
	v_lshlrev_b32_e32 v1, 2, v1
	s_lshl_b32 s2, s4, 13
	s_or_b32 s25, s24, 0x80
	v_bitop3_b32 v4, v4, s6, v5 bitop3:0xde
	v_lshl_or_b32 v142, s4, 6, v1
	s_or_b32 s4, s2, 0x800
	s_or_b32 s6, s2, 0x1000
	s_or_b32 s7, s2, 0x1800
	v_lshl_or_b32 v144, s3, 4, v0
	s_lshr_b32 s3, s25, 1
	v_lshlrev_b32_e32 v10, 6, v195
	s_add_u32 s18, s8, 0x4442000
	v_lshrrev_b32_e32 v9, 2, v252
	v_and_b32_e32 v10, 0x3c0, v10
	s_addc_u32 s19, s22, 0
	s_mov_b32 s15, 0x20000
	v_bitop3_b32 v3, v2, v5, v3 bitop3:0x36
	v_or_b32_e32 v143, s24, v0
	v_and_b32_e32 v9, 4, v9
	v_bitop3_b32 v2, v10, v5, v2 bitop3:0x36
	v_mov_b32_e32 v145, 0x800
	v_or_b32_e32 v147, s3, v0
	s_add_u32 s20, s8, 0x2040000
	v_cndmask_b32_e64 v0, 0, 1, s[0:1]
	s_mov_b32 s14, 0x2200000
	s_mov_b32 s10, 0xc00000
	s_mov_b32 s11, s15
	v_and_or_b32 v146, v1, 4, v145
	v_or_b32_e32 v148, 0x800, v9
	v_or_b32_e32 v149, 0x801, v9
	v_or_b32_e32 v150, 0x802, v9
	v_or_b32_e32 v151, 0x803, v9
	v_add_u32_e32 v152, 0x10000, v138
	v_add_u32_e32 v153, 0x12000, v138
	v_add_u32_e32 v154, 0x14000, v138
	v_add_u32_e32 v155, 0x16000, v138
	s_movk_i32 s26, 0x4000
	v_add_u32_e32 v156, 0x4000, v138
	v_add_u32_e32 v157, 0x6000, v138
	v_add_u32_e32 v158, 0x18000, v138
	v_add_u32_e32 v159, 0x1a000, v138
	v_add_u32_e32 v160, 0x8000, v138
	v_add_u32_e32 v161, 0xa000, v138
	v_add_u32_e32 v162, 0x1c000, v138
	v_add_u32_e32 v163, 0x1e000, v138
	v_add_u32_e32 v164, 0xc000, v138
	v_add_u32_e32 v165, 0xe000, v138
	s_addc_u32 s21, s22, 0
	s_movk_i32 s27, 0xcd
	v_add_u32_e32 v166, s5, v6
	v_add_u32_e32 v167, s2, v3
	v_add_u32_e32 v168, s4, v2
	v_add_u32_e32 v169, s6, v2
	v_add_u32_e32 v170, s7, v2
	v_add_u32_e32 v171, s5, v7
	v_add_u32_e32 v172, s5, v8
	v_add_u32_e32 v173, s5, v4
	s_movk_i32 s28, 0x3080
	v_mov_b32_e32 v129, 0
	s_movk_i32 s29, 0x7cd
	s_movk_i32 s30, 0x7ce
	s_movk_i32 s31, 0x7cf
	s_movk_i32 s34, 0x7dd
	s_movk_i32 s35, 0x7de
	s_movk_i32 s36, 0x7df
	s_movk_i32 s37, 0x7ed
	s_movk_i32 s38, 0x7ee
	s_movk_i32 s39, 0x7ef
	s_movk_i32 s40, 0x7fd
	s_movk_i32 s41, 0x7fe
	s_movk_i32 s42, 0x7ff
	v_cmp_ne_u32_e64 s[2:3], 1, v0
	s_mov_b32 s43, s78
	s_add_u32 s8, s84, 0xc00000
	s_addc_u32 s0, s85, 0
	s_and_b32 s9, s0, 0xffff
	s_mov_b32 s10, 0x400000
	s_add_u32 s12, s84, 0x11262000
	s_addc_u32 s0, s85, 0
	s_and_b32 s13, s0, 0xffff
	s_mov_b32 s14, 0x4400000
	s_add_u32 s18, s84, 0x15662000
	s_addc_u32 s19, s85, 0
	s_and_b32 s0, s78, 7
	s_lshr_b32 s1, s78, 3
	s_lshl_b32 s4, s0, 3
	s_lshr_b32 s0, s1, 2
	s_add_i32 s4, s4, s0
	s_and_b32 s1, s1, 3
	s_lshl_b32 s5, s4, 20
	s_lshl_b32 s6, s1, 20
	s_mov_b32 s7, s5
	v_writelane_b32 v255, s4, 51
	v_writelane_b32 v255, s1, 52
	v_mov_b32_e32 v200, v252
	v_lshrrev_b32_e32 v201, 2, v200
	v_and_b32_e32 v202, 3, v200
	v_lshl_add_u32 v201, s4, 8, v201
	v_lshlrev_b32_e32 v201, 8, v201
	v_lshl_add_u32 v203, v202, 6, v201
; #define WAIT_V(n) asm volatile("s_waitcnt vmcnt(" #n ")" ::: "memory")
; #define BAR __builtin_amdgcn_s_barrier()
;     ...
;     if (NH > 0) {
;       for (int idx = tid; idx < BM * NH; idx += NTHR) {
;         int row = idx / NH, h = idx % NH;
;         const float* pp = parts + (size_t)(m0 + row) * 64 + h * (64 / NH);
;         float s = 0.f;
; #pragma unroll
;         for (int q = 0; q < 64 / NH; ++q) s += pp[q];
;         rstdS[idx] = rsqrtf(s / (float)(K / NH) + 1e-6f);
;       }
; template <int EPI>
; __device__ void gemm8_phase(const Params& p, const u16* __restrict__ A, const u16* __restrict__ Bt, const int K, const int nN,
;                             unsigned char* smem, const int rep) {
;     ...
;     STAGE(SB(0, 0), Bt, bcol, 0); STAGE(SA(0, 0), A, brow, 0);
;     STAGE(SB(0, 1), Bt, bcol + HALF, 0); STAGE(SA(0, 1), A, brow + HALF, 0);
;     if (wr == 1) BAR;
;     WAIT_V(4); BAR;
;     STAGE(SB(1, 0), Bt, bcol, 1); STAGE(SA(1, 0), A, brow, 1); STAGE(SB(1, 1), Bt, bcol + HALF, 1);
;     WAIT_V(6); BAR;
	global_load_dwordx4 v[208:211], v203, s[18:19]
	global_load_dwordx4 v[212:215], v203, s[18:19] offset:16
	global_load_dwordx4 v[216:219], v203, s[18:19] offset:32
	global_load_dwordx4 v[220:223], v203, s[18:19] offset:48
	v_add_u32_e32 v200, 512, v252
	v_lshrrev_b32_e32 v201, 2, v200
	v_and_b32_e32 v202, 3, v200
	v_lshl_add_u32 v201, s4, 8, v201
	v_lshlrev_b32_e32 v201, 8, v201
	v_lshl_add_u32 v204, v202, 6, v201
	global_load_dwordx4 v[224:227], v204, s[18:19]
	global_load_dwordx4 v[228:231], v204, s[18:19] offset:16
	global_load_dwordx4 v[232:235], v204, s[18:19] offset:32
	global_load_dwordx4 v[236:239], v204, s[18:19] offset:48
	v_readfirstlane_b32 s44, v152
	s_nop 1
	s_mov_b32 m0, s44
	s_nop 0
	buffer_load_dwordx4 v139, s[8:11], s6 offen lds
	v_readfirstlane_b32 s44, v153
	s_nop 1
	s_mov_b32 m0, s44
	s_nop 0
	buffer_load_dwordx4 v141, s[8:11], s6 offen lds
	v_readfirstlane_b32 s44, v138
	s_nop 1
	s_mov_b32 m0, s44
	s_nop 0
	buffer_load_dwordx4 v139, s[12:15], s5 offen lds
	v_readfirstlane_b32 s44, v140
	s_nop 1
	s_mov_b32 m0, s44
	s_nop 0
	buffer_load_dwordx4 v141, s[12:15], s5 offen lds
	s_or_b32 s45, s6, 0x80000
	v_readfirstlane_b32 s44, v154
	s_nop 1
	s_mov_b32 m0, s44
	s_nop 0
	buffer_load_dwordx4 v139, s[8:11], s45 offen lds
	v_readfirstlane_b32 s44, v155
	s_nop 1
	s_mov_b32 m0, s44
	s_nop 0
	buffer_load_dwordx4 v141, s[8:11], s45 offen lds
	s_or_b32 s45, s5, 0x80000
	v_readfirstlane_b32 s44, v156
	s_nop 1
	s_mov_b32 m0, s44
	s_nop 0
	buffer_load_dwordx4 v139, s[12:15], s45 offen lds
	v_readfirstlane_b32 s44, v157
	s_nop 1
	s_mov_b32 m0, s44
	s_nop 0
	buffer_load_dwordx4 v141, s[12:15], s45 offen lds
	s_waitcnt vmcnt(8)
	v_add_f32_e32 v200, 0, v208
	v_add_f32_e32 v200, v200, v209
	v_add_f32_e32 v200, v200, v210
	v_add_f32_e32 v200, v200, v211
	v_add_f32_e32 v200, v200, v212
	v_add_f32_e32 v200, v200, v213
	v_add_f32_e32 v200, v200, v214
	v_add_f32_e32 v200, v200, v215
	v_add_f32_e32 v200, v200, v216
	v_add_f32_e32 v200, v200, v217
	v_add_f32_e32 v200, v200, v218
	v_add_f32_e32 v200, v200, v219
	v_add_f32_e32 v200, v200, v220
	v_add_f32_e32 v200, v200, v221
	v_add_f32_e32 v200, v200, v222
	v_add_f32_e32 v200, v200, v223
	v_mov_b32_e32 v201, 0x358637bd
	v_fmac_f32_e32 v201, 0x3b000000, v200
	v_rsq_f32_e32 v201, v201
	v_lshlrev_b32_e32 v202, 2, v252
	v_add_u32_e32 v202, 0x20000, v202
	ds_write_b32 v202, v201
	v_add_f32_e32 v200, 0, v224
	v_add_f32_e32 v200, v200, v225
	v_add_f32_e32 v200, v200, v226
	v_add_f32_e32 v200, v200, v227
	v_add_f32_e32 v200, v200, v228
	v_add_f32_e32 v200, v200, v229
	v_add_f32_e32 v200, v200, v230
	v_add_f32_e32 v200, v200, v231
	v_add_f32_e32 v200, v200, v232
	v_add_f32_e32 v200, v200, v233
	v_add_f32_e32 v200, v200, v234
	v_add_f32_e32 v200, v200, v235
	v_add_f32_e32 v200, v200, v236
	v_add_f32_e32 v200, v200, v237
	v_add_f32_e32 v200, v200, v238
	v_add_f32_e32 v200, v200, v239
	v_mov_b32_e32 v201, 0x358637bd
	v_fmac_f32_e32 v201, 0x3b000000, v200
	v_rsq_f32_e32 v201, v201
	v_lshlrev_b32_e32 v202, 2, v252
	v_add_u32_e32 v202, 0x20800, v202
	ds_write_b32 v202, v201
	v_and_b32_e32 v128, 15, v195
	v_lshrrev_b32_e32 v129, 2, v252
	v_and_b32_e32 v129, 64, v129
	v_add_u32_e32 v128, v128, v129
	v_lshlrev_b32_e32 v128, 4, v128
	v_add_u32_e32 v128, 0x20000, v128
	s_waitcnt lgkmcnt(0)
	s_and_b64 vcc, exec, s[2:3]
	s_cbranch_vccnz .Lq3_201
	s_barrier
.Lq3_201:
	v_readfirstlane_b32 s45, v158
	s_or_b32 s44, s6, 0x80
	s_mov_b32 m0, s45
	v_readfirstlane_b32 s45, v159
	s_waitcnt vmcnt(4)
	s_barrier
	buffer_load_dwordx4 v139, s[8:11], s44 offen lds
	s_mov_b32 m0, s45
	v_readfirstlane_b32 s45, v160
	buffer_load_dwordx4 v141, s[8:11], s44 offen lds
	s_or_b32 s44, s5, 0x80
	s_mov_b32 m0, s45
	v_readfirstlane_b32 s45, v161
	buffer_load_dwordx4 v139, s[12:15], s44 offen lds
	s_mov_b32 m0, s45
	v_readfirstlane_b32 s45, v162
	buffer_load_dwordx4 v141, s[12:15], s44 offen lds
	s_or_b32 s44, s6, 0x80080
	s_mov_b32 m0, s45
	v_readfirstlane_b32 s45, v163
	buffer_load_dwordx4 v139, s[8:11], s44 offen lds
	s_mov_b32 m0, s45
	s_nop 0
	buffer_load_dwordx4 v141, s[8:11], s44 offen lds
	s_waitcnt vmcnt(6)
	s_nop 0
	v_mov_b32_e32 v0, 0
	s_nop 0
	s_mov_b32 s33, -2
	s_mov_b32 s44, 0
	v_mov_b32_e32 v1, v0
	v_mov_b32_e32 v2, v0
	v_mov_b32_e32 v3, v0
	v_mov_b32_e32 v4, v0
	v_mov_b32_e32 v5, v0
	v_mov_b32_e32 v6, v0
	v_mov_b32_e32 v7, v0
	v_mov_b32_e32 v8, v0
	v_mov_b32_e32 v9, v0
	v_mov_b32_e32 v10, v0
	v_mov_b32_e32 v11, v0
	v_mov_b32_e32 v12, v0
	v_mov_b32_e32 v13, v0
	v_mov_b32_e32 v14, v0
	v_mov_b32_e32 v15, v0
	v_mov_b32_e32 v16, v0
	v_mov_b32_e32 v17, v0
	v_mov_b32_e32 v18, v0
	v_mov_b32_e32 v19, v0
	v_mov_b32_e32 v20, v0
	v_mov_b32_e32 v21, v0
	v_mov_b32_e32 v22, v0
	v_mov_b32_e32 v23, v0
	v_mov_b32_e32 v24, v0
	v_mov_b32_e32 v25, v0
	v_mov_b32_e32 v26, v0
	v_mov_b32_e32 v27, v0
	v_mov_b32_e32 v28, v0
	v_mov_b32_e32 v29, v0
	v_mov_b32_e32 v30, v0
	v_mov_b32_e32 v31, v0
	v_mov_b32_e32 v32, v0
	v_mov_b32_e32 v33, v0
	v_mov_b32_e32 v34, v0
	v_mov_b32_e32 v35, v0
	v_mov_b32_e32 v36, v0
	v_mov_b32_e32 v37, v0
	v_mov_b32_e32 v38, v0
	v_mov_b32_e32 v39, v0
	v_mov_b32_e32 v40, v0
	v_mov_b32_e32 v41, v0
	v_mov_b32_e32 v42, v0
	v_mov_b32_e32 v43, v0
	v_mov_b32_e32 v44, v0
	v_mov_b32_e32 v45, v0
	v_mov_b32_e32 v46, v0
	v_mov_b32_e32 v47, v0
	v_mov_b32_e32 v48, v0
	v_mov_b32_e32 v49, v0
	v_mov_b32_e32 v50, v0
	v_mov_b32_e32 v51, v0
	v_mov_b32_e32 v52, v0
	v_mov_b32_e32 v53, v0
	v_mov_b32_e32 v54, v0
	v_mov_b32_e32 v55, v0
	v_mov_b32_e32 v56, v0
	v_mov_b32_e32 v57, v0
	v_mov_b32_e32 v58, v0
	v_mov_b32_e32 v59, v0
	v_mov_b32_e32 v60, v0
	v_mov_b32_e32 v61, v0
	v_mov_b32_e32 v62, v0
	v_mov_b32_e32 v63, v0
	v_mov_b32_e32 v64, v0
	v_mov_b32_e32 v65, v0
; #define WAIT_L(n) asm volatile("s_waitcnt lgkmcnt(" #n ")" ::: "memory")
; #define BAR __builtin_amdgcn_s_barrier()
; #define SCHED __builtin_amdgcn_sched_barrier(0)
; template <int EPI>
; __device__ void gemm8_phase(const Params& p, const u16* __restrict__ A, const u16* __restrict__ Bt, const int K, const int nN,
;                             unsigned char* smem, const int rep) {
;     ...
;     f32x4 acc[2][2][4][2];
; #pragma unroll
;     for (int a = 0; a < 2; ++a)
; #pragma unroll
;       for (int b = 0; b < 2; ++b)
; #pragma unroll
;         for (int m = 0; m < 4; ++m)
; #pragma unroll
;           for (int n = 0; n < 2; ++n) acc[a][b][m][n] = (f32x4){0.f, 0.f, 0.f, 0.f};
;     ...
;     for (int t = 0; t < nt - 2; t += 2) {
;       LDB(B0, 0, 0); SCHED; LDA(At, 0, 0); STAGE(SA(1, 1), A, brow + HALF, t + 1);
;       WAIT_L(8); BAR; WAIT_L(0); MMA(0, 0, At, B0); BAR; SCHED;
	v_mov_b32_e32 v66, v0
	v_mov_b32_e32 v67, v0
	v_mov_b32_e32 v68, v0
	v_mov_b32_e32 v69, v0
	v_mov_b32_e32 v70, v0
	v_mov_b32_e32 v71, v0
	v_mov_b32_e32 v72, v0
	v_mov_b32_e32 v73, v0
	v_mov_b32_e32 v74, v0
	v_mov_b32_e32 v75, v0
	v_mov_b32_e32 v76, v0
	v_mov_b32_e32 v77, v0
	v_mov_b32_e32 v78, v0
	v_mov_b32_e32 v79, v0
	v_mov_b32_e32 v80, v0
	v_mov_b32_e32 v81, v0
	v_mov_b32_e32 v82, v0
	v_mov_b32_e32 v83, v0
	v_mov_b32_e32 v84, v0
	v_mov_b32_e32 v85, v0
	v_mov_b32_e32 v86, v0
	v_mov_b32_e32 v87, v0
	v_mov_b32_e32 v88, v0
	v_mov_b32_e32 v89, v0
	v_mov_b32_e32 v90, v0
	v_mov_b32_e32 v91, v0
	v_mov_b32_e32 v92, v0
	v_mov_b32_e32 v93, v0
	v_mov_b32_e32 v94, v0
	v_mov_b32_e32 v95, v0
	v_mov_b32_e32 v96, v0
	v_mov_b32_e32 v97, v0
	v_mov_b32_e32 v98, v0
	v_mov_b32_e32 v99, v0
	v_mov_b32_e32 v100, v0
	v_mov_b32_e32 v101, v0
	v_mov_b32_e32 v102, v0
	v_mov_b32_e32 v103, v0
	v_mov_b32_e32 v104, v0
	v_mov_b32_e32 v105, v0
	v_mov_b32_e32 v106, v0
	v_mov_b32_e32 v107, v0
	v_mov_b32_e32 v108, v0
	v_mov_b32_e32 v109, v0
	v_mov_b32_e32 v110, v0
	v_mov_b32_e32 v111, v0
	v_mov_b32_e32 v112, v0
	v_mov_b32_e32 v113, v0
	v_mov_b32_e32 v114, v0
	v_mov_b32_e32 v115, v0
	v_mov_b32_e32 v116, v0
	v_mov_b32_e32 v117, v0
	v_mov_b32_e32 v118, v0
	v_mov_b32_e32 v119, v0
	v_mov_b32_e32 v120, v0
	v_mov_b32_e32 v121, v0
	v_mov_b32_e32 v122, v0
	v_mov_b32_e32 v123, v0
	v_mov_b32_e32 v124, v0
	v_mov_b32_e32 v125, v0
	v_mov_b32_e32 v126, v0
	v_mov_b32_e32 v127, v0
	s_barrier
.Lq3_202:
	ds_read_b128 v[130:133], v166
	ds_read_b128 v[174:177], v166 offset:1024
	ds_read_b128 v[178:181], v166 offset:2048
	ds_read_b128 v[182:185], v166 offset:3072
	s_add_i32 s45, s7, s44
	v_readfirstlane_b32 s47, v164
	s_or_b32 s46, s45, 0x80080
	s_mov_b32 m0, s47
	v_readfirstlane_b32 s47, v165
	ds_read_b128 v[186:189], v167
	ds_read_b128 v[190:193], v167 offset:1024
	ds_read_b128 v[196:199], v168
	ds_read_b128 v[200:203], v168 offset:1024
	ds_read_b128 v[204:207], v169
	ds_read_b128 v[208:211], v169 offset:1024
	ds_read_b128 v[212:215], v170
	ds_read_b128 v[216:219], v170 offset:1024
	buffer_load_dwordx4 v139, s[12:15], s46 offen lds
	s_mov_b32 m0, s47
	s_nop 0
	buffer_load_dwordx4 v141, s[12:15], s46 offen lds
	s_waitcnt lgkmcnt(8)
	s_barrier
	s_waitcnt lgkmcnt(0)
	s_setprio 1
	s_waitcnt lgkmcnt(7)
	v_mfma_f32_16x16x32_bf16 v[124:127], v[130:133], v[186:189], v[124:127]
	v_mfma_f32_16x16x32_bf16 v[120:123], v[178:181], v[186:189], v[120:123]
	s_waitcnt lgkmcnt(5)
	v_mfma_f32_16x16x32_bf16 v[116:119], v[130:133], v[196:199], v[116:119]
	v_mfma_f32_16x16x32_bf16 v[112:115], v[178:181], v[196:199], v[112:115]
	s_waitcnt lgkmcnt(3)
	v_mfma_f32_16x16x32_bf16 v[108:111], v[130:133], v[204:207], v[108:111]
	v_mfma_f32_16x16x32_bf16 v[104:107], v[178:181], v[204:207], v[104:107]
	s_waitcnt lgkmcnt(1)
	v_mfma_f32_16x16x32_bf16 v[100:103], v[130:133], v[212:215], v[100:103]
	v_mfma_f32_16x16x32_bf16 v[96:99], v[178:181], v[212:215], v[96:99]
	v_mfma_f32_16x16x32_bf16 v[124:127], v[174:177], v[190:193], v[124:127]
	v_mfma_f32_16x16x32_bf16 v[120:123], v[182:185], v[190:193], v[120:123]
	v_mfma_f32_16x16x32_bf16 v[116:119], v[174:177], v[200:203], v[116:119]
	v_mfma_f32_16x16x32_bf16 v[112:115], v[182:185], v[200:203], v[112:115]
	v_mfma_f32_16x16x32_bf16 v[108:111], v[174:177], v[208:211], v[108:111]
	v_mfma_f32_16x16x32_bf16 v[104:107], v[182:185], v[208:211], v[104:107]
	s_waitcnt lgkmcnt(0)
	v_mfma_f32_16x16x32_bf16 v[100:103], v[174:177], v[216:219], v[100:103]
	v_mfma_f32_16x16x32_bf16 v[96:99], v[182:185], v[216:219], v[96:99]
	s_setprio 0
	s_barrier
	s_add_i32 s46, s6, s44
	v_readfirstlane_b32 s48, v152
	s_add_i32 s47, s46, 0x100
	s_mov_b32 m0, s48
	v_readfirstlane_b32 s48, v153
	ds_read_b128 v[220:223], v171
	ds_read_b128 v[224:227], v171 offset:1024
	ds_read_b128 v[228:231], v171 offset:2048
	ds_read_b128 v[232:235], v171 offset:3072
	buffer_load_dwordx4 v139, s[8:11], s47 offen lds
	s_mov_b32 m0, s48
	s_nop 0
	buffer_load_dwordx4 v141, s[8:11], s47 offen lds
	s_barrier
	s_waitcnt lgkmcnt(0)
	s_setprio 1
	s_waitcnt lgkmcnt(3)
	v_mfma_f32_16x16x32_bf16 v[92:95], v[220:223], v[186:189], v[92:95]
	s_waitcnt lgkmcnt(1)
	v_mfma_f32_16x16x32_bf16 v[88:91], v[228:231], v[186:189], v[88:91]
	v_mfma_f32_16x16x32_bf16 v[84:87], v[220:223], v[196:199], v[84:87]
	v_mfma_f32_16x16x32_bf16 v[80:83], v[228:231], v[196:199], v[80:83]
	v_mfma_f32_16x16x32_bf16 v[76:79], v[220:223], v[204:207], v[76:79]
	v_mfma_f32_16x16x32_bf16 v[72:75], v[228:231], v[204:207], v[72:75]
	v_mfma_f32_16x16x32_bf16 v[68:71], v[220:223], v[212:215], v[68:71]
	v_mfma_f32_16x16x32_bf16 v[64:67], v[228:231], v[212:215], v[64:67]
	v_mfma_f32_16x16x32_bf16 v[92:95], v[224:227], v[190:193], v[92:95]
	s_waitcnt lgkmcnt(0)
	v_mfma_f32_16x16x32_bf16 v[88:91], v[232:235], v[190:193], v[88:91]
	v_mfma_f32_16x16x32_bf16 v[84:87], v[224:227], v[200:203], v[84:87]
	v_mfma_f32_16x16x32_bf16 v[80:83], v[232:235], v[200:203], v[80:83]
	v_mfma_f32_16x16x32_bf16 v[76:79], v[224:227], v[208:211], v[76:79]
	v_mfma_f32_16x16x32_bf16 v[72:75], v[232:235], v[208:211], v[72:75]
	v_mfma_f32_16x16x32_bf16 v[68:71], v[224:227], v[216:219], v[68:71]
	v_mfma_f32_16x16x32_bf16 v[64:67], v[232:235], v[216:219], v[64:67]
	s_setprio 0
	v_readfirstlane_b32 s48, v138
	s_add_i32 s47, s45, 0x100
	s_mov_b32 m0, s48
	v_readfirstlane_b32 s48, v140
	s_barrier
	ds_read_b128 v[186:189], v167 offset:16384
	ds_read_b128 v[190:193], v167 offset:17408
	ds_read_b128 v[196:199], v168 offset:16384
	ds_read_b128 v[200:203], v168 offset:17408
	ds_read_b128 v[204:207], v169 offset:16384
	ds_read_b128 v[208:211], v169 offset:17408
	ds_read_b128 v[212:215], v170 offset:16384
	ds_read_b128 v[216:219], v170 offset:17408
	buffer_load_dwordx4 v139, s[12:15], s47 offen lds
	s_mov_b32 m0, s48
	s_nop 0
	buffer_load_dwordx4 v141, s[12:15], s47 offen lds
	s_barrier
; #define WAIT_V(n) asm volatile("s_waitcnt vmcnt(" #n ")" ::: "memory")
; #define WAIT_L(n) asm volatile("s_waitcnt lgkmcnt(" #n ")" ::: "memory")
; #define BAR __builtin_amdgcn_s_barrier()
; #define SCHED __builtin_amdgcn_sched_barrier(0)
; template <int EPI>
; __device__ void gemm8_phase(const Params& p, const u16* __restrict__ A, const u16* __restrict__ Bt, const int K, const int nN,
;                             unsigned char* smem, const int rep) {
;     ...
;       WAIT_L(8); BAR; WAIT_L(0); MMA(0, 0, At, B0); BAR; SCHED;
;       LDB(B1, 0, 1); STAGE(SB(0, 0), Bt, bcol, t + 2);
;       BAR; WAIT_L(0); MMA(0, 1, At, B1); BAR;
;       LDA(At, 0, 1); STAGE(SA(0, 0), A, brow, t + 2);
;       BAR; WAIT_L(0); MMA(1, 0, At, B0); BAR; SCHED;
;       STAGE(SB(0, 1), Bt, bcol + HALF, t + 2);
;       WAIT_V(6); BAR; MMA(1, 1, At, B1); BAR;
;       LDB(B0, 1, 0); SCHED; LDA(At, 1, 0); STAGE(SA(0, 1), A, brow + HALF, t + 2);
;       WAIT_L(8); BAR; WAIT_L(0); MMA(0, 0, At, B0); BAR; SCHED;
	s_waitcnt lgkmcnt(0)
	s_setprio 1
	s_waitcnt lgkmcnt(7)
	v_mfma_f32_16x16x32_bf16 v[60:63], v[130:133], v[186:189], v[60:63]
	v_mfma_f32_16x16x32_bf16 v[56:59], v[178:181], v[186:189], v[56:59]
	s_waitcnt lgkmcnt(5)
	v_mfma_f32_16x16x32_bf16 v[52:55], v[130:133], v[196:199], v[52:55]
	v_mfma_f32_16x16x32_bf16 v[48:51], v[178:181], v[196:199], v[48:51]
	s_waitcnt lgkmcnt(3)
	v_mfma_f32_16x16x32_bf16 v[44:47], v[130:133], v[204:207], v[44:47]
	v_mfma_f32_16x16x32_bf16 v[40:43], v[178:181], v[204:207], v[40:43]
	s_waitcnt lgkmcnt(1)
	v_mfma_f32_16x16x32_bf16 v[36:39], v[130:133], v[212:215], v[36:39]
	v_mfma_f32_16x16x32_bf16 v[32:35], v[178:181], v[212:215], v[32:35]
	v_mfma_f32_16x16x32_bf16 v[60:63], v[174:177], v[190:193], v[60:63]
	v_mfma_f32_16x16x32_bf16 v[56:59], v[182:185], v[190:193], v[56:59]
	v_mfma_f32_16x16x32_bf16 v[52:55], v[174:177], v[200:203], v[52:55]
	v_mfma_f32_16x16x32_bf16 v[48:51], v[182:185], v[200:203], v[48:51]
	v_mfma_f32_16x16x32_bf16 v[44:47], v[174:177], v[208:211], v[44:47]
	v_mfma_f32_16x16x32_bf16 v[40:43], v[182:185], v[208:211], v[40:43]
	s_waitcnt lgkmcnt(0)
	v_mfma_f32_16x16x32_bf16 v[36:39], v[174:177], v[216:219], v[36:39]
	v_mfma_f32_16x16x32_bf16 v[32:35], v[182:185], v[216:219], v[32:35]
	s_setprio 0
	s_barrier
	v_readfirstlane_b32 s48, v154
	s_add_i32 s47, s46, 0x80100
	s_mov_b32 m0, s48
	v_readfirstlane_b32 s48, v155
	buffer_load_dwordx4 v139, s[8:11], s47 offen lds
	s_mov_b32 m0, s48
	s_nop 0
	buffer_load_dwordx4 v141, s[8:11], s47 offen lds
	s_waitcnt vmcnt(6)
	s_barrier
	s_setprio 1
	v_mfma_f32_16x16x32_bf16 v[28:31], v[220:223], v[186:189], v[28:31]
	v_mfma_f32_16x16x32_bf16 v[24:27], v[228:231], v[186:189], v[24:27]
	v_mfma_f32_16x16x32_bf16 v[20:23], v[220:223], v[196:199], v[20:23]
	v_mfma_f32_16x16x32_bf16 v[16:19], v[228:231], v[196:199], v[16:19]
	v_mfma_f32_16x16x32_bf16 v[12:15], v[220:223], v[204:207], v[12:15]
	v_mfma_f32_16x16x32_bf16 v[8:11], v[228:231], v[204:207], v[8:11]
	v_mfma_f32_16x16x32_bf16 v[4:7], v[220:223], v[212:215], v[4:7]
	v_mfma_f32_16x16x32_bf16 v[0:3], v[228:231], v[212:215], v[0:3]
	v_mfma_f32_16x16x32_bf16 v[28:31], v[224:227], v[190:193], v[28:31]
	v_mfma_f32_16x16x32_bf16 v[24:27], v[232:235], v[190:193], v[24:27]
	v_mfma_f32_16x16x32_bf16 v[20:23], v[224:227], v[200:203], v[20:23]
	v_mfma_f32_16x16x32_bf16 v[16:19], v[232:235], v[200:203], v[16:19]
	v_mfma_f32_16x16x32_bf16 v[12:15], v[224:227], v[208:211], v[12:15]
	v_mfma_f32_16x16x32_bf16 v[8:11], v[232:235], v[208:211], v[8:11]
	v_mfma_f32_16x16x32_bf16 v[4:7], v[224:227], v[216:219], v[4:7]
	v_mfma_f32_16x16x32_bf16 v[0:3], v[232:235], v[216:219], v[0:3]
	s_setprio 0
	s_barrier
	ds_read_b128 v[130:133], v172
	ds_read_b128 v[174:177], v172 offset:1024
	ds_read_b128 v[178:181], v172 offset:2048
	ds_read_b128 v[182:185], v172 offset:3072
	v_readfirstlane_b32 s48, v156
	s_add_i32 s47, s45, 0x80100
	s_mov_b32 m0, s48
	v_readfirstlane_b32 s48, v157
	ds_read_b128 v[186:189], v167 offset:32768
	ds_read_b128 v[190:193], v167 offset:33792
	ds_read_b128 v[196:199], v168 offset:32768
	ds_read_b128 v[200:203], v168 offset:33792
	ds_read_b128 v[204:207], v169 offset:32768
	ds_read_b128 v[208:211], v169 offset:33792
	ds_read_b128 v[212:215], v170 offset:32768
	ds_read_b128 v[216:219], v170 offset:33792
	buffer_load_dwordx4 v139, s[12:15], s47 offen lds
	s_mov_b32 m0, s48
	s_nop 0
	buffer_load_dwordx4 v141, s[12:15], s47 offen lds
	s_waitcnt lgkmcnt(8)
	s_barrier
	s_waitcnt lgkmcnt(0)
	s_setprio 1
	s_waitcnt lgkmcnt(7)
	v_mfma_f32_16x16x32_bf16 v[124:127], v[130:133], v[186:189], v[124:127]
	v_mfma_f32_16x16x32_bf16 v[120:123], v[178:181], v[186:189], v[120:123]
	s_waitcnt lgkmcnt(5)
	v_mfma_f32_16x16x32_bf16 v[116:119], v[130:133], v[196:199], v[116:119]
	v_mfma_f32_16x16x32_bf16 v[112:115], v[178:181], v[196:199], v[112:115]
	s_waitcnt lgkmcnt(3)
	v_mfma_f32_16x16x32_bf16 v[108:111], v[130:133], v[204:207], v[108:111]
	v_mfma_f32_16x16x32_bf16 v[104:107], v[178:181], v[204:207], v[104:107]
	s_waitcnt lgkmcnt(1)
	v_mfma_f32_16x16x32_bf16 v[100:103], v[130:133], v[212:215], v[100:103]
	v_mfma_f32_16x16x32_bf16 v[96:99], v[178:181], v[212:215], v[96:99]
	v_mfma_f32_16x16x32_bf16 v[124:127], v[174:177], v[190:193], v[124:127]
	v_mfma_f32_16x16x32_bf16 v[120:123], v[182:185], v[190:193], v[120:123]
	v_mfma_f32_16x16x32_bf16 v[116:119], v[174:177], v[200:203], v[116:119]
	v_mfma_f32_16x16x32_bf16 v[112:115], v[182:185], v[200:203], v[112:115]
	v_mfma_f32_16x16x32_bf16 v[108:111], v[174:177], v[208:211], v[108:111]
	v_mfma_f32_16x16x32_bf16 v[104:107], v[182:185], v[208:211], v[104:107]
	s_waitcnt lgkmcnt(0)
	v_mfma_f32_16x16x32_bf16 v[100:103], v[174:177], v[216:219], v[100:103]
	v_mfma_f32_16x16x32_bf16 v[96:99], v[182:185], v[216:219], v[96:99]
	s_setprio 0
	s_barrier
	v_readfirstlane_b32 s48, v158
	s_add_i32 s47, s46, 0x180
	s_mov_b32 m0, s48
	v_readfirstlane_b32 s48, v159
	ds_read_b128 v[220:223], v173
	ds_read_b128 v[224:227], v173 offset:1024
	ds_read_b128 v[228:231], v173 offset:2048
	ds_read_b128 v[232:235], v173 offset:3072
	buffer_load_dwordx4 v139, s[8:11], s47 offen lds
	s_mov_b32 m0, s48
	s_nop 0
	buffer_load_dwordx4 v141, s[8:11], s47 offen lds
	s_barrier
; #define WAIT_V(n) asm volatile("s_waitcnt vmcnt(" #n ")" ::: "memory")
; #define WAIT_L(n) asm volatile("s_waitcnt lgkmcnt(" #n ")" ::: "memory")
; #define BAR __builtin_amdgcn_s_barrier()
; #define SCHED __builtin_amdgcn_sched_barrier(0)
; template <int EPI>
; __device__ void gemm8_phase(const Params& p, const u16* __restrict__ A, const u16* __restrict__ Bt, const int K, const int nN,
;                             unsigned char* smem, const int rep) {
;     ...
;       WAIT_L(8); BAR; WAIT_L(0); MMA(0, 0, At, B0); BAR; SCHED;
;       LDB(B1, 1, 1); STAGE(SB(1, 0), Bt, bcol, t + 3);
;       BAR; WAIT_L(0); MMA(0, 1, At, B1); BAR;
;       LDA(At, 1, 1); STAGE(SA(1, 0), A, brow, t + 3);
;       BAR; WAIT_L(0); MMA(1, 0, At, B0); BAR; SCHED;
;       STAGE(SB(1, 1), Bt, bcol + HALF, t + 3);
;       WAIT_V(6); BAR; MMA(1, 1, At, B1); BAR;
	s_waitcnt lgkmcnt(0)
	s_setprio 1
	s_waitcnt lgkmcnt(3)
	v_mfma_f32_16x16x32_bf16 v[92:95], v[220:223], v[186:189], v[92:95]
	s_waitcnt lgkmcnt(1)
	v_mfma_f32_16x16x32_bf16 v[88:91], v[228:231], v[186:189], v[88:91]
	v_mfma_f32_16x16x32_bf16 v[84:87], v[220:223], v[196:199], v[84:87]
	v_mfma_f32_16x16x32_bf16 v[80:83], v[228:231], v[196:199], v[80:83]
	v_mfma_f32_16x16x32_bf16 v[76:79], v[220:223], v[204:207], v[76:79]
	v_mfma_f32_16x16x32_bf16 v[72:75], v[228:231], v[204:207], v[72:75]
	v_mfma_f32_16x16x32_bf16 v[68:71], v[220:223], v[212:215], v[68:71]
	v_mfma_f32_16x16x32_bf16 v[64:67], v[228:231], v[212:215], v[64:67]
	v_mfma_f32_16x16x32_bf16 v[92:95], v[224:227], v[190:193], v[92:95]
	s_waitcnt lgkmcnt(0)
	v_mfma_f32_16x16x32_bf16 v[88:91], v[232:235], v[190:193], v[88:91]
	v_mfma_f32_16x16x32_bf16 v[84:87], v[224:227], v[200:203], v[84:87]
	v_mfma_f32_16x16x32_bf16 v[80:83], v[232:235], v[200:203], v[80:83]
	v_mfma_f32_16x16x32_bf16 v[76:79], v[224:227], v[208:211], v[76:79]
	v_mfma_f32_16x16x32_bf16 v[72:75], v[232:235], v[208:211], v[72:75]
	v_mfma_f32_16x16x32_bf16 v[68:71], v[224:227], v[216:219], v[68:71]
	v_mfma_f32_16x16x32_bf16 v[64:67], v[232:235], v[216:219], v[64:67]
	s_setprio 0
	v_readfirstlane_b32 s47, v160
	s_addk_i32 s45, 0x180
	s_mov_b32 m0, s47
	v_readfirstlane_b32 s47, v161
	s_barrier
	ds_read_b128 v[186:189], v167 offset:49152
	ds_read_b128 v[190:193], v167 offset:50176
	ds_read_b128 v[196:199], v168 offset:49152
	ds_read_b128 v[200:203], v168 offset:50176
	ds_read_b128 v[204:207], v169 offset:49152
	ds_read_b128 v[208:211], v169 offset:50176
	ds_read_b128 v[212:215], v170 offset:49152
	ds_read_b128 v[216:219], v170 offset:50176
	buffer_load_dwordx4 v139, s[12:15], s45 offen lds
	s_mov_b32 m0, s47
	s_nop 0
	buffer_load_dwordx4 v141, s[12:15], s45 offen lds
	s_barrier
	s_waitcnt lgkmcnt(0)
	s_setprio 1
	s_waitcnt lgkmcnt(7)
	v_mfma_f32_16x16x32_bf16 v[60:63], v[130:133], v[186:189], v[60:63]
	v_mfma_f32_16x16x32_bf16 v[56:59], v[178:181], v[186:189], v[56:59]
	s_waitcnt lgkmcnt(5)
	v_mfma_f32_16x16x32_bf16 v[52:55], v[130:133], v[196:199], v[52:55]
	v_mfma_f32_16x16x32_bf16 v[48:51], v[178:181], v[196:199], v[48:51]
	s_waitcnt lgkmcnt(3)
	v_mfma_f32_16x16x32_bf16 v[44:47], v[130:133], v[204:207], v[44:47]
	v_mfma_f32_16x16x32_bf16 v[40:43], v[178:181], v[204:207], v[40:43]
	s_waitcnt lgkmcnt(1)
	v_mfma_f32_16x16x32_bf16 v[36:39], v[130:133], v[212:215], v[36:39]
	v_mfma_f32_16x16x32_bf16 v[32:35], v[178:181], v[212:215], v[32:35]
	v_mfma_f32_16x16x32_bf16 v[60:63], v[174:177], v[190:193], v[60:63]
	v_mfma_f32_16x16x32_bf16 v[56:59], v[182:185], v[190:193], v[56:59]
	v_mfma_f32_16x16x32_bf16 v[52:55], v[174:177], v[200:203], v[52:55]
	v_mfma_f32_16x16x32_bf16 v[48:51], v[182:185], v[200:203], v[48:51]
	v_mfma_f32_16x16x32_bf16 v[44:47], v[174:177], v[208:211], v[44:47]
	v_mfma_f32_16x16x32_bf16 v[40:43], v[182:185], v[208:211], v[40:43]
	s_waitcnt lgkmcnt(0)
	v_mfma_f32_16x16x32_bf16 v[36:39], v[174:177], v[216:219], v[36:39]
	v_mfma_f32_16x16x32_bf16 v[32:35], v[182:185], v[216:219], v[32:35]
	s_setprio 0
	s_barrier
	v_readfirstlane_b32 s45, v162
	s_add_i32 s46, s46, 0x80180
	s_mov_b32 m0, s45
	v_readfirstlane_b32 s45, v163
	buffer_load_dwordx4 v139, s[8:11], s46 offen lds
	s_mov_b32 m0, s45
	s_nop 0
	buffer_load_dwordx4 v141, s[8:11], s46 offen lds
	s_waitcnt vmcnt(6)
	s_barrier
	s_setprio 1
	v_mfma_f32_16x16x32_bf16 v[28:31], v[220:223], v[186:189], v[28:31]
	v_mfma_f32_16x16x32_bf16 v[24:27], v[228:231], v[186:189], v[24:27]
	v_mfma_f32_16x16x32_bf16 v[20:23], v[220:223], v[196:199], v[20:23]
	v_mfma_f32_16x16x32_bf16 v[16:19], v[228:231], v[196:199], v[16:19]
	v_mfma_f32_16x16x32_bf16 v[12:15], v[220:223], v[204:207], v[12:15]
	v_mfma_f32_16x16x32_bf16 v[8:11], v[228:231], v[204:207], v[8:11]
	v_mfma_f32_16x16x32_bf16 v[4:7], v[220:223], v[212:215], v[4:7]
	v_mfma_f32_16x16x32_bf16 v[0:3], v[228:231], v[212:215], v[0:3]
	v_mfma_f32_16x16x32_bf16 v[28:31], v[224:227], v[190:193], v[28:31]
	v_mfma_f32_16x16x32_bf16 v[24:27], v[232:235], v[190:193], v[24:27]
	v_mfma_f32_16x16x32_bf16 v[20:23], v[224:227], v[200:203], v[20:23]
	v_mfma_f32_16x16x32_bf16 v[16:19], v[232:235], v[200:203], v[16:19]
	v_mfma_f32_16x16x32_bf16 v[12:15], v[224:227], v[208:211], v[12:15]
	v_mfma_f32_16x16x32_bf16 v[8:11], v[232:235], v[208:211], v[8:11]
	v_mfma_f32_16x16x32_bf16 v[4:7], v[224:227], v[216:219], v[4:7]
	v_mfma_f32_16x16x32_bf16 v[0:3], v[232:235], v[216:219], v[0:3]
	s_setprio 0
	s_add_i32 s48, s33, 4
	s_and_b32 s48, s48, 7
	s_cmp_lg_u32 s48, 0
	s_cbranch_scc1 .Lq3_nosc
;     ...
;       if (NH > 0) {
;         const int per = KT / NH;
;         if (((kt + 1) % per) == 0) {
;           const int h = (kt + 1) / per - 1;
; #pragma unroll
;           for (int mf = 0; mf < 4; ++mf)
; #pragma unroll
;             for (int r = 0; r < 4; ++r) {
;               float s = rstdS[(wm * 64 + mf * 16 + 4 * g + r) * NH + h];
; #pragma unroll
;               for (int nf = 0; nf < 4; ++nf) {
;                 accT[mf][nf][r] += s * acc[mf][nf][r];
;                 acc[mf][nf][r] = 0.f;
;               }
;             }
;         }
	s_add_i32 s48, s33, 4
	s_lshr_b32 s48, s48, 3
	s_sub_i32 s48, s48, 1
	s_lshl_b32 s48, s48, 2
	v_add_u32_e32 v220, s48, v128
	ds_read_b32 v221, v220
	ds_read_b32 v222, v220 offset:4
	ds_read_b32 v223, v220 offset:256
	ds_read_b32 v224, v220 offset:260
	ds_read_b32 v225, v220 offset:512
	ds_read_b32 v226, v220 offset:516
	ds_read_b32 v227, v220 offset:768
	ds_read_b32 v228, v220 offset:772
	ds_read_b32 v229, v220 offset:2048
	ds_read_b32 v230, v220 offset:2052
	ds_read_b32 v231, v220 offset:2304
	ds_read_b32 v232, v220 offset:2308
	ds_read_b32 v233, v220 offset:2560
	ds_read_b32 v234, v220 offset:2564
	ds_read_b32 v235, v220 offset:2816
	ds_read_b32 v236, v220 offset:2820
	s_waitcnt lgkmcnt(0)
	v_rcp_f32_e32 v222, v222
	v_rcp_f32_e32 v224, v224
	v_rcp_f32_e32 v226, v226
	v_rcp_f32_e32 v228, v228
	v_rcp_f32_e32 v230, v230
	v_rcp_f32_e32 v232, v232
	v_rcp_f32_e32 v234, v234
	v_rcp_f32_e32 v236, v236
	s_nop 0
	v_mul_f32_e32 v221, v221, v222
	v_mul_f32_e32 v223, v223, v224
	v_mul_f32_e32 v225, v225, v226
	v_mul_f32_e32 v227, v227, v228
	v_mul_f32_e32 v229, v229, v230
	v_mul_f32_e32 v231, v231, v232
	v_mul_f32_e32 v233, v233, v234
	v_mul_f32_e32 v235, v235, v236
	v_mul_f32_e32 v124, v221, v124
	v_mul_f32_e32 v125, v221, v125
	v_mul_f32_e32 v126, v221, v126
	v_mul_f32_e32 v127, v221, v127
	v_mul_f32_e32 v120, v221, v120
	v_mul_f32_e32 v121, v221, v121
	v_mul_f32_e32 v122, v221, v122
	v_mul_f32_e32 v123, v221, v123
	v_mul_f32_e32 v92, v221, v92
	v_mul_f32_e32 v93, v221, v93
	v_mul_f32_e32 v94, v221, v94
	v_mul_f32_e32 v95, v221, v95
	v_mul_f32_e32 v88, v221, v88
	v_mul_f32_e32 v89, v221, v89
	v_mul_f32_e32 v90, v221, v90
	v_mul_f32_e32 v91, v221, v91
	v_mul_f32_e32 v116, v223, v116
	v_mul_f32_e32 v117, v223, v117
	v_mul_f32_e32 v118, v223, v118
	v_mul_f32_e32 v119, v223, v119
	v_mul_f32_e32 v112, v223, v112
	v_mul_f32_e32 v113, v223, v113
	v_mul_f32_e32 v114, v223, v114
	v_mul_f32_e32 v115, v223, v115
	v_mul_f32_e32 v84, v223, v84
	v_mul_f32_e32 v85, v223, v85
	v_mul_f32_e32 v86, v223, v86
	v_mul_f32_e32 v87, v223, v87
	v_mul_f32_e32 v80, v223, v80
	v_mul_f32_e32 v81, v223, v81
	v_mul_f32_e32 v82, v223, v82
	v_mul_f32_e32 v83, v223, v83
	v_mul_f32_e32 v108, v225, v108
	v_mul_f32_e32 v109, v225, v109
	v_mul_f32_e32 v110, v225, v110
	v_mul_f32_e32 v111, v225, v111
	v_mul_f32_e32 v104, v225, v104
	v_mul_f32_e32 v105, v225, v105
	v_mul_f32_e32 v106, v225, v106
	v_mul_f32_e32 v107, v225, v107
	v_mul_f32_e32 v76, v225, v76
	v_mul_f32_e32 v77, v225, v77
	v_mul_f32_e32 v78, v225, v78
	v_mul_f32_e32 v79, v225, v79
	v_mul_f32_e32 v72, v225, v72
	v_mul_f32_e32 v73, v225, v73
	v_mul_f32_e32 v74, v225, v74
	v_mul_f32_e32 v75, v225, v75
	v_mul_f32_e32 v100, v227, v100
	v_mul_f32_e32 v101, v227, v101
	v_mul_f32_e32 v102, v227, v102
	v_mul_f32_e32 v103, v227, v103
	v_mul_f32_e32 v96, v227, v96
	v_mul_f32_e32 v97, v227, v97
	v_mul_f32_e32 v98, v227, v98
	v_mul_f32_e32 v99, v227, v99
	v_mul_f32_e32 v68, v227, v68
	v_mul_f32_e32 v69, v227, v69
	v_mul_f32_e32 v70, v227, v70
	v_mul_f32_e32 v71, v227, v71
	v_mul_f32_e32 v64, v227, v64
	v_mul_f32_e32 v65, v227, v65
	v_mul_f32_e32 v66, v227, v66
	v_mul_f32_e32 v67, v227, v67
	v_mul_f32_e32 v60, v229, v60
	v_mul_f32_e32 v61, v229, v61
	v_mul_f32_e32 v62, v229, v62
	v_mul_f32_e32 v63, v229, v63
	v_mul_f32_e32 v56, v229, v56
	v_mul_f32_e32 v57, v229, v57
	v_mul_f32_e32 v58, v229, v58
	v_mul_f32_e32 v59, v229, v59
	v_mul_f32_e32 v28, v229, v28
	v_mul_f32_e32 v29, v229, v29
	v_mul_f32_e32 v30, v229, v30
	v_mul_f32_e32 v31, v229, v31
	v_mul_f32_e32 v24, v229, v24
	v_mul_f32_e32 v25, v229, v25
	v_mul_f32_e32 v26, v229, v26
	v_mul_f32_e32 v27, v229, v27
	v_mul_f32_e32 v52, v231, v52
	v_mul_f32_e32 v53, v231, v53
	v_mul_f32_e32 v54, v231, v54
	v_mul_f32_e32 v55, v231, v55
	v_mul_f32_e32 v48, v231, v48
	v_mul_f32_e32 v49, v231, v49
	v_mul_f32_e32 v50, v231, v50
	v_mul_f32_e32 v51, v231, v51
	v_mul_f32_e32 v20, v231, v20
	v_mul_f32_e32 v21, v231, v21
	v_mul_f32_e32 v22, v231, v22
	v_mul_f32_e32 v23, v231, v23
	v_mul_f32_e32 v16, v231, v16
	v_mul_f32_e32 v17, v231, v17
	v_mul_f32_e32 v18, v231, v18
	v_mul_f32_e32 v19, v231, v19
	v_mul_f32_e32 v44, v233, v44
	v_mul_f32_e32 v45, v233, v45
	v_mul_f32_e32 v46, v233, v46
	v_mul_f32_e32 v47, v233, v47
	v_mul_f32_e32 v40, v233, v40
	v_mul_f32_e32 v41, v233, v41
	v_mul_f32_e32 v42, v233, v42
	v_mul_f32_e32 v43, v233, v43
	v_mul_f32_e32 v12, v233, v12
	v_mul_f32_e32 v13, v233, v13
	v_mul_f32_e32 v14, v233, v14
	v_mul_f32_e32 v15, v233, v15
	v_mul_f32_e32 v8, v233, v8
	v_mul_f32_e32 v9, v233, v9
	v_mul_f32_e32 v10, v233, v10
	v_mul_f32_e32 v11, v233, v11
	v_mul_f32_e32 v36, v235, v36
	v_mul_f32_e32 v37, v235, v37
	v_mul_f32_e32 v38, v235, v38
	v_mul_f32_e32 v39, v235, v39
	v_mul_f32_e32 v32, v235, v32
	v_mul_f32_e32 v33, v235, v33
	v_mul_f32_e32 v34, v235, v34
	v_mul_f32_e32 v35, v235, v35
	v_mul_f32_e32 v4, v235, v4
	v_mul_f32_e32 v5, v235, v5
	v_mul_f32_e32 v6, v235, v6
	v_mul_f32_e32 v7, v235, v7
	v_mul_f32_e32 v0, v235, v0
	v_mul_f32_e32 v1, v235, v1
	v_mul_f32_e32 v2, v235, v2
	v_mul_f32_e32 v3, v235, v3
; #define WAIT_V(n) asm volatile("s_waitcnt vmcnt(" #n ")" ::: "memory")
; #define WAIT_L(n) asm volatile("s_waitcnt lgkmcnt(" #n ")" ::: "memory")
; #define BAR __builtin_amdgcn_s_barrier()
; #define SCHED __builtin_amdgcn_sched_barrier(0)
; template <int EPI>
; __device__ void gemm8_phase(const Params& p, const u16* __restrict__ A, const u16* __restrict__ Bt, const int K, const int nN,
;                             unsigned char* smem, const int rep) {
;     ...
;     for (int t = 0; t < nt - 2; t += 2) {
;       LDB(B0, 0, 0); SCHED; LDA(At, 0, 0); STAGE(SA(1, 1), A, brow + HALF, t + 1);
;       WAIT_L(8); BAR; WAIT_L(0); MMA(0, 0, At, B0); BAR; SCHED;
;       LDB(B1, 0, 1); STAGE(SB(0, 0), Bt, bcol, t + 2);
;       BAR; WAIT_L(0); MMA(0, 1, At, B1); BAR;
;       LDA(At, 0, 1); STAGE(SA(0, 0), A, brow, t + 2);
;       BAR; WAIT_L(0); MMA(1, 0, At, B0); BAR; SCHED;
;       STAGE(SB(0, 1), Bt, bcol + HALF, t + 2);
;       WAIT_V(6); BAR; MMA(1, 1, At, B1); BAR;
;       LDB(B0, 1, 0); SCHED; LDA(At, 1, 0); STAGE(SA(0, 1), A, brow + HALF, t + 2);
;       WAIT_L(8); BAR; WAIT_L(0); MMA(0, 0, At, B0); BAR; SCHED;
;       LDB(B1, 1, 1); STAGE(SB(1, 0), Bt, bcol, t + 3);
;       BAR; WAIT_L(0); MMA(0, 1, At, B1); BAR;
;       LDA(At, 1, 1); STAGE(SA(1, 0), A, brow, t + 3);
;       BAR; WAIT_L(0); MMA(1, 0, At, B0); BAR; SCHED;
;       STAGE(SB(1, 1), Bt, bcol + HALF, t + 3);
;       WAIT_V(6); BAR; MMA(1, 1, At, B1); BAR;
;     }
;     {
;       LDB(B0, 0, 0); LDA(At, 0, 0); STAGE(SA(1, 1), A, brow + HALF, nt - 1);
;       BAR; WAIT_L(0); MMA(0, 0, At, B0); BAR; SCHED;
;       LDB(B1, 0, 1); BAR; WAIT_L(0); MMA(0, 1, At, B1); BAR; SCHED;
;       LDA(At, 0, 1); WAIT_V(4); BAR; WAIT_L(0); MMA(1, 0, At, B0); MMA(1, 1, At, B1); BAR; SCHED;
;     }
.Lq3_nosc:
	s_add_i32 s33, s33, 2
	s_addk_i32 s44, 0x100
	s_cmp_lt_u32 s33, 28
	s_barrier
	s_cbranch_scc1 .Lq3_202
	v_readfirstlane_b32 s6, v164
	s_or_b32 s5, s5, 0x80f80
	s_mov_b32 m0, s6
	v_readfirstlane_b32 s6, v165
	ds_read_b128 v[130:133], v166
	ds_read_b128 v[174:177], v166 offset:1024
	ds_read_b128 v[178:181], v166 offset:2048
	ds_read_b128 v[182:185], v166 offset:3072
	ds_read_b128 v[186:189], v167
	ds_read_b128 v[190:193], v167 offset:1024
	ds_read_b128 v[196:199], v168
	ds_read_b128 v[200:203], v168 offset:1024
	ds_read_b128 v[204:207], v169
	ds_read_b128 v[208:211], v169 offset:1024
	ds_read_b128 v[212:215], v170
	ds_read_b128 v[216:219], v170 offset:1024
	buffer_load_dwordx4 v139, s[12:15], s5 offen lds
	s_mov_b32 m0, s6
	s_nop 0
	buffer_load_dwordx4 v141, s[12:15], s5 offen lds
	s_barrier
	s_waitcnt lgkmcnt(0)
	s_setprio 1
	s_waitcnt lgkmcnt(7)
	v_mfma_f32_16x16x32_bf16 v[124:127], v[130:133], v[186:189], v[124:127]
	s_waitcnt lgkmcnt(5)
	v_mfma_f32_16x16x32_bf16 v[116:119], v[130:133], v[196:199], v[116:119]
	v_mfma_f32_16x16x32_bf16 v[112:115], v[178:181], v[196:199], v[112:115]
	s_waitcnt lgkmcnt(1)
	v_mfma_f32_16x16x32_bf16 v[100:103], v[130:133], v[212:215], v[100:103]
	v_mfma_f32_16x16x32_bf16 v[96:99], v[178:181], v[212:215], v[96:99]
	v_mfma_f32_16x16x32_bf16 v[124:127], v[174:177], v[190:193], v[124:127]
	v_mfma_f32_16x16x32_bf16 v[120:123], v[178:181], v[186:189], v[120:123]
	v_mfma_f32_16x16x32_bf16 v[116:119], v[174:177], v[200:203], v[116:119]
	v_mfma_f32_16x16x32_bf16 v[112:115], v[182:185], v[200:203], v[112:115]
	v_mfma_f32_16x16x32_bf16 v[108:111], v[130:133], v[204:207], v[108:111]
	v_mfma_f32_16x16x32_bf16 v[104:107], v[178:181], v[204:207], v[104:107]
	s_waitcnt lgkmcnt(0)
	v_mfma_f32_16x16x32_bf16 v[100:103], v[174:177], v[216:219], v[100:103]
	v_mfma_f32_16x16x32_bf16 v[96:99], v[182:185], v[216:219], v[96:99]
	v_mfma_f32_16x16x32_bf16 v[220:223], v[182:185], v[190:193], v[120:123]
	v_mfma_f32_16x16x32_bf16 v[224:227], v[174:177], v[208:211], v[108:111]
	v_mfma_f32_16x16x32_bf16 v[228:231], v[182:185], v[208:211], v[104:107]
	s_setprio 0
	s_barrier
	s_nop 0
	ds_read_b128 v[104:107], v171
	ds_read_b128 v[108:111], v171 offset:1024
	ds_read_b128 v[120:123], v171 offset:2048
	ds_read_b128 v[232:235], v171 offset:3072
	s_barrier
	s_waitcnt lgkmcnt(0)
	s_setprio 1
	s_waitcnt lgkmcnt(3)
	v_mfma_f32_16x16x32_bf16 v[84:87], v[104:107], v[196:199], v[84:87]
	s_waitcnt lgkmcnt(1)
	v_mfma_f32_16x16x32_bf16 v[80:83], v[120:123], v[196:199], v[80:83]
	v_mfma_f32_16x16x32_bf16 v[68:71], v[104:107], v[212:215], v[68:71]
	v_mfma_f32_16x16x32_bf16 v[92:95], v[104:107], v[186:189], v[92:95]
	v_mfma_f32_16x16x32_bf16 v[88:91], v[120:123], v[186:189], v[88:91]
	v_mfma_f32_16x16x32_bf16 v[84:87], v[108:111], v[200:203], v[84:87]
	s_waitcnt lgkmcnt(0)
	v_mfma_f32_16x16x32_bf16 v[80:83], v[232:235], v[200:203], v[80:83]
	v_mfma_f32_16x16x32_bf16 v[76:79], v[104:107], v[204:207], v[76:79]
	v_mfma_f32_16x16x32_bf16 v[72:75], v[120:123], v[204:207], v[72:75]
	v_mfma_f32_16x16x32_bf16 v[68:71], v[108:111], v[216:219], v[68:71]
	v_mfma_f32_16x16x32_bf16 v[64:67], v[120:123], v[212:215], v[64:67]
	v_mfma_f32_16x16x32_bf16 v[236:239], v[108:111], v[190:193], v[92:95]
	v_mfma_f32_16x16x32_bf16 v[186:189], v[232:235], v[190:193], v[88:91]
	v_mfma_f32_16x16x32_bf16 v[190:193], v[108:111], v[208:211], v[76:79]
	v_mfma_f32_16x16x32_bf16 v[196:199], v[232:235], v[208:211], v[72:75]
	v_mfma_f32_16x16x32_bf16 v[200:203], v[232:235], v[216:219], v[64:67]
	s_setprio 0
	s_barrier
	s_nop 0
	ds_read_b128 v[64:67], v167 offset:16384
	ds_read_b128 v[72:75], v167 offset:17408
	ds_read_b128 v[76:79], v168 offset:16384
	ds_read_b128 v[88:91], v168 offset:17408
	ds_read_b128 v[92:95], v169 offset:16384
	ds_read_b128 v[204:207], v169 offset:17408
	ds_read_b128 v[208:211], v170 offset:16384
	ds_read_b128 v[212:215], v170 offset:17408
	s_waitcnt vmcnt(4)
	s_barrier
	s_waitcnt lgkmcnt(0)
	s_setprio 1
	s_waitcnt lgkmcnt(7)
	v_mfma_f32_16x16x32_bf16 v[60:63], v[130:133], v[64:67], v[60:63]
	s_waitcnt lgkmcnt(5)
	v_mfma_f32_16x16x32_bf16 v[52:55], v[130:133], v[76:79], v[52:55]
	v_mfma_f32_16x16x32_bf16 v[48:51], v[178:181], v[76:79], v[48:51]
	s_waitcnt lgkmcnt(1)
	v_mfma_f32_16x16x32_bf16 v[36:39], v[130:133], v[208:211], v[36:39]
	v_mfma_f32_16x16x32_bf16 v[32:35], v[178:181], v[208:211], v[32:35]
	v_mfma_f32_16x16x32_bf16 v[60:63], v[174:177], v[72:75], v[60:63]
	v_mfma_f32_16x16x32_bf16 v[56:59], v[178:181], v[64:67], v[56:59]
	v_mfma_f32_16x16x32_bf16 v[52:55], v[174:177], v[88:91], v[52:55]
	v_mfma_f32_16x16x32_bf16 v[48:51], v[182:185], v[88:91], v[48:51]
	v_mfma_f32_16x16x32_bf16 v[44:47], v[130:133], v[92:95], v[44:47]
	v_mfma_f32_16x16x32_bf16 v[40:43], v[178:181], v[92:95], v[40:43]
	s_waitcnt lgkmcnt(0)
	v_mfma_f32_16x16x32_bf16 v[36:39], v[174:177], v[212:215], v[36:39]
	v_mfma_f32_16x16x32_bf16 v[32:35], v[182:185], v[212:215], v[32:35]
	v_mfma_f32_16x16x32_bf16 v[216:219], v[182:185], v[72:75], v[56:59]
	v_mfma_f32_16x16x32_bf16 v[240:243], v[174:177], v[204:207], v[44:47]
	v_mfma_f32_16x16x32_bf16 v[244:247], v[182:185], v[204:207], v[40:43]
	s_setprio 0
	s_setprio 1
	v_mfma_f32_16x16x32_bf16 v[20:23], v[104:107], v[76:79], v[20:23]
	v_mfma_f32_16x16x32_bf16 v[16:19], v[120:123], v[76:79], v[16:19]
	v_mfma_f32_16x16x32_bf16 v[4:7], v[104:107], v[208:211], v[4:7]
	v_mfma_f32_16x16x32_bf16 v[28:31], v[104:107], v[64:67], v[28:31]
	v_mfma_f32_16x16x32_bf16 v[24:27], v[120:123], v[64:67], v[24:27]
	v_mfma_f32_16x16x32_bf16 v[20:23], v[108:111], v[88:91], v[20:23]
	v_mfma_f32_16x16x32_bf16 v[16:19], v[232:235], v[88:91], v[16:19]
	v_mfma_f32_16x16x32_bf16 v[12:15], v[104:107], v[92:95], v[12:15]
	v_mfma_f32_16x16x32_bf16 v[8:11], v[120:123], v[92:95], v[8:11]
	v_mfma_f32_16x16x32_bf16 v[4:7], v[108:111], v[212:215], v[4:7]
	v_mfma_f32_16x16x32_bf16 v[0:3], v[120:123], v[208:211], v[0:3]
	v_mfma_f32_16x16x32_bf16 v[130:133], v[108:111], v[72:75], v[28:31]
	v_mfma_f32_16x16x32_bf16 v[174:177], v[232:235], v[72:75], v[24:27]
	v_mfma_f32_16x16x32_bf16 v[178:181], v[108:111], v[204:207], v[12:15]
	v_mfma_f32_16x16x32_bf16 v[182:185], v[232:235], v[204:207], v[8:11]
	v_mfma_f32_16x16x32_bf16 v[204:207], v[232:235], v[212:215], v[0:3]
	s_setprio 0
	s_barrier
; #define WAIT_V(n) asm volatile("s_waitcnt vmcnt(" #n ")" ::: "memory")
; #define WAIT_L(n) asm volatile("s_waitcnt lgkmcnt(" #n ")" ::: "memory")
; #define BAR __builtin_amdgcn_s_barrier()
; #define SCHED __builtin_amdgcn_sched_barrier(0)
; template <int EPI>
; __device__ void gemm8_phase(const Params& p, const u16* __restrict__ A, const u16* __restrict__ Bt, const int K, const int nN,
;                             unsigned char* smem, const int rep) {
;     ...
;       BAR; WAIT_L(0); MMA(0, 0, At, B0); BAR; SCHED;
;       LDB(B1, 0, 1); BAR; WAIT_L(0); MMA(0, 1, At, B1); BAR; SCHED;
;       LDA(At, 0, 1); WAIT_V(4); BAR; WAIT_L(0); MMA(1, 0, At, B0); MMA(1, 1, At, B1); BAR; SCHED;
;     }
;     {
;       LDB(B0, 1, 0); LDA(At, 1, 0); WAIT_V(2); BAR; WAIT_L(0); MMA(0, 0, At, B0); BAR; SCHED;
;       LDB(B1, 1, 1); WAIT_V(0); BAR; WAIT_L(0); MMA(0, 1, At, B1); BAR; SCHED;
;       LDA(At, 1, 1); BAR; WAIT_L(0); MMA(1, 0, At, B0); MMA(1, 1, At, B1); BAR; SCHED;
;     }
;     if (wr == 0) BAR;
	s_nop 0
	ds_read_b128 v[0:3], v172
	ds_read_b128 v[8:11], v172 offset:1024
	ds_read_b128 v[12:15], v172 offset:2048
	ds_read_b128 v[208:211], v172 offset:3072
	ds_read_b128 v[24:27], v167 offset:32768
	ds_read_b128 v[28:31], v167 offset:33792
	ds_read_b128 v[40:43], v168 offset:32768
	ds_read_b128 v[44:47], v168 offset:33792
	ds_read_b128 v[56:59], v169 offset:32768
	ds_read_b128 v[64:67], v169 offset:33792
	ds_read_b128 v[212:215], v170 offset:32768
	ds_read_b128 v[232:235], v170 offset:33792
	s_waitcnt vmcnt(2)
	s_barrier
	s_waitcnt lgkmcnt(0)
	s_setprio 1
	s_waitcnt lgkmcnt(7)
	v_mfma_f32_16x16x32_bf16 v[72:75], v[0:3], v[24:27], v[124:127]
	s_waitcnt lgkmcnt(6)
	v_mfma_f32_16x16x32_bf16 v[120:123], v[8:11], v[28:31], v[72:75]
	v_mfma_f32_16x16x32_bf16 v[72:75], v[12:15], v[24:27], v[220:223]
	v_mfma_f32_16x16x32_bf16 v[124:127], v[208:211], v[28:31], v[72:75]
	s_waitcnt lgkmcnt(5)
	v_mfma_f32_16x16x32_bf16 v[72:75], v[0:3], v[40:43], v[116:119]
	s_waitcnt lgkmcnt(4)
	v_mfma_f32_16x16x32_bf16 v[104:107], v[8:11], v[44:47], v[72:75]
	v_mfma_f32_16x16x32_bf16 v[72:75], v[12:15], v[40:43], v[112:115]
	v_mfma_f32_16x16x32_bf16 v[108:111], v[208:211], v[44:47], v[72:75]
	s_waitcnt lgkmcnt(3)
	v_mfma_f32_16x16x32_bf16 v[72:75], v[0:3], v[56:59], v[224:227]
	s_waitcnt lgkmcnt(2)
	v_mfma_f32_16x16x32_bf16 v[88:91], v[8:11], v[64:67], v[72:75]
	v_mfma_f32_16x16x32_bf16 v[72:75], v[12:15], v[56:59], v[228:231]
	v_mfma_f32_16x16x32_bf16 v[92:95], v[208:211], v[64:67], v[72:75]
	s_waitcnt lgkmcnt(1)
	v_mfma_f32_16x16x32_bf16 v[72:75], v[0:3], v[212:215], v[100:103]
	v_mfma_f32_16x16x32_bf16 v[76:79], v[12:15], v[212:215], v[96:99]
	s_waitcnt lgkmcnt(0)
	v_mfma_f32_16x16x32_bf16 v[72:75], v[8:11], v[232:235], v[72:75]
	v_mfma_f32_16x16x32_bf16 v[76:79], v[208:211], v[232:235], v[76:79]
	s_setprio 0
	s_barrier
	ds_read_b128 v[220:223], v173
	ds_read_b128 v[224:227], v173 offset:1024
	ds_read_b128 v[228:231], v173 offset:2048
	ds_read_b128 v[248:251], v173 offset:3072
	s_waitcnt vmcnt(0)
	s_barrier
	s_waitcnt lgkmcnt(0)
	s_setprio 1
	s_waitcnt lgkmcnt(3)
	v_mfma_f32_16x16x32_bf16 v[96:99], v[220:223], v[24:27], v[236:239]
	s_waitcnt lgkmcnt(1)
	v_mfma_f32_16x16x32_bf16 v[24:27], v[228:231], v[24:27], v[186:189]
	s_waitcnt lgkmcnt(0)
	v_mfma_f32_16x16x32_bf16 v[116:119], v[248:251], v[28:31], v[24:27]
	v_mfma_f32_16x16x32_bf16 v[24:27], v[220:223], v[40:43], v[84:87]
	v_mfma_f32_16x16x32_bf16 v[112:115], v[224:227], v[28:31], v[96:99]
	v_mfma_f32_16x16x32_bf16 v[96:99], v[224:227], v[44:47], v[24:27]
	v_mfma_f32_16x16x32_bf16 v[24:27], v[228:231], v[40:43], v[80:83]
	v_mfma_f32_16x16x32_bf16 v[100:103], v[248:251], v[44:47], v[24:27]
	v_mfma_f32_16x16x32_bf16 v[24:27], v[220:223], v[56:59], v[190:193]
	v_mfma_f32_16x16x32_bf16 v[80:83], v[224:227], v[64:67], v[24:27]
	v_mfma_f32_16x16x32_bf16 v[24:27], v[228:231], v[56:59], v[196:199]
	v_mfma_f32_16x16x32_bf16 v[84:87], v[248:251], v[64:67], v[24:27]
	v_mfma_f32_16x16x32_bf16 v[24:27], v[220:223], v[212:215], v[68:71]
	v_mfma_f32_16x16x32_bf16 v[64:67], v[224:227], v[232:235], v[24:27]
	v_mfma_f32_16x16x32_bf16 v[24:27], v[228:231], v[212:215], v[200:203]
	v_mfma_f32_16x16x32_bf16 v[68:71], v[248:251], v[232:235], v[24:27]
	s_setprio 0
	s_barrier
	ds_read_b128 v[186:189], v167 offset:49152
	ds_read_b128 v[190:193], v167 offset:50176
	ds_read_b128 v[196:199], v168 offset:49152
	ds_read_b128 v[200:203], v168 offset:50176
	ds_read_b128 v[212:215], v169 offset:49152
	ds_read_b128 v[232:235], v169 offset:50176
	ds_read_b128 v[236:239], v170 offset:49152
	ds_read_b128 v[134:137], v170 offset:50176
	s_barrier
	s_waitcnt lgkmcnt(0)
	s_setprio 1
	s_waitcnt lgkmcnt(7)
	v_mfma_f32_16x16x32_bf16 v[24:27], v[0:3], v[186:189], v[60:63]
	s_waitcnt lgkmcnt(6)
	v_mfma_f32_16x16x32_bf16 v[56:59], v[8:11], v[190:193], v[24:27]
	v_mfma_f32_16x16x32_bf16 v[24:27], v[12:15], v[186:189], v[216:219]
	v_mfma_f32_16x16x32_bf16 v[60:63], v[208:211], v[190:193], v[24:27]
	s_waitcnt lgkmcnt(5)
	v_mfma_f32_16x16x32_bf16 v[24:27], v[0:3], v[196:199], v[52:55]
	s_waitcnt lgkmcnt(4)
	v_mfma_f32_16x16x32_bf16 v[40:43], v[8:11], v[200:203], v[24:27]
	v_mfma_f32_16x16x32_bf16 v[24:27], v[12:15], v[196:199], v[48:51]
	v_mfma_f32_16x16x32_bf16 v[44:47], v[208:211], v[200:203], v[24:27]
	s_waitcnt lgkmcnt(3)
	v_mfma_f32_16x16x32_bf16 v[24:27], v[0:3], v[212:215], v[240:243]
	s_waitcnt lgkmcnt(1)
	v_mfma_f32_16x16x32_bf16 v[0:3], v[0:3], v[236:239], v[36:39]
	v_mfma_f32_16x16x32_bf16 v[24:27], v[8:11], v[232:235], v[24:27]
	v_mfma_f32_16x16x32_bf16 v[28:31], v[12:15], v[212:215], v[244:247]
	s_waitcnt lgkmcnt(0)
	v_mfma_f32_16x16x32_bf16 v[8:11], v[8:11], v[134:137], v[0:3]
	v_mfma_f32_16x16x32_bf16 v[0:3], v[12:15], v[236:239], v[32:35]
	v_mfma_f32_16x16x32_bf16 v[28:31], v[208:211], v[232:235], v[28:31]
	v_mfma_f32_16x16x32_bf16 v[12:15], v[208:211], v[134:137], v[0:3]
	s_setprio 0
	s_setprio 1
	v_mfma_f32_16x16x32_bf16 v[0:3], v[220:223], v[186:189], v[130:133]
	v_mfma_f32_16x16x32_bf16 v[48:51], v[224:227], v[190:193], v[0:3]
	v_mfma_f32_16x16x32_bf16 v[0:3], v[228:231], v[186:189], v[174:177]
	v_mfma_f32_16x16x32_bf16 v[52:55], v[248:251], v[190:193], v[0:3]
	v_mfma_f32_16x16x32_bf16 v[0:3], v[220:223], v[196:199], v[20:23]
	v_mfma_f32_16x16x32_bf16 v[32:35], v[224:227], v[200:203], v[0:3]
	v_mfma_f32_16x16x32_bf16 v[0:3], v[228:231], v[196:199], v[16:19]
	v_mfma_f32_16x16x32_bf16 v[36:39], v[248:251], v[200:203], v[0:3]
	v_mfma_f32_16x16x32_bf16 v[0:3], v[220:223], v[212:215], v[178:181]
	v_mfma_f32_16x16x32_bf16 v[16:19], v[224:227], v[232:235], v[0:3]
	v_mfma_f32_16x16x32_bf16 v[0:3], v[228:231], v[212:215], v[182:185]
	v_mfma_f32_16x16x32_bf16 v[20:23], v[248:251], v[232:235], v[0:3]
	v_mfma_f32_16x16x32_bf16 v[0:3], v[220:223], v[236:239], v[4:7]
	v_mfma_f32_16x16x32_bf16 v[4:7], v[228:231], v[236:239], v[204:207]
	v_mfma_f32_16x16x32_bf16 v[0:3], v[224:227], v[134:137], v[0:3]
	v_mfma_f32_16x16x32_bf16 v[4:7], v[248:251], v[134:137], v[4:7]
	s_setprio 0
	s_barrier
	s_andn2_b64 vcc, exec, s[16:17]
	s_cbranch_vccnz .Lq3_205
	s_barrier
;     ...
;       if (NH > 0) {
;         const int per = KT / NH;
;         if (((kt + 1) % per) == 0) {
;           const int h = (kt + 1) / per - 1;
; #pragma unroll
;           for (int mf = 0; mf < 4; ++mf)
; #pragma unroll
;             for (int r = 0; r < 4; ++r) {
;               float s = rstdS[(wm * 64 + mf * 16 + 4 * g + r) * NH + h];
; #pragma unroll
;               for (int nf = 0; nf < 4; ++nf) {
;                 accT[mf][nf][r] += s * acc[mf][nf][r];
;                 acc[mf][nf][r] = 0.f;
;               }
;             }
;         }
;     ...
;       if (EPI == 1) {
; #pragma unroll
;         for (int r = 0; r < 4; ++r) {
;           const int row = m0 + wm * 64 + mf * 16 + 4 * g + r;
; #pragma unroll
;           for (int nf = 0; nf < 4; ++nf) {
;             const int col = n0 + wn * 64 + nf * 16 + l15;
;             rvv[r][nf] = resid ? resid[(size_t)row * 1024 + col] : xrow(p, row)[col];
;           }
;         }
;       }
; #pragma unroll
;       for (int r = 0; r < 4; ++r) {
;         const int row = m0 + wm * 64 + mf * 16 + 4 * g + r;
;         if (EPI == 0) {
;           u16* proj = (u16*)(p.ws + OFF_PROJ) + (size_t)row * PROJ_LD;
;           if (n0 < 2048) {
;             const float2* rope = (const float2*)(p.ws + OFF_ROPE);
;             const int pi = row < NPROMPT ? (row & 2047) : 2048 + ((row - NPROMPT) & 7);
; #pragma unroll
;             for (int np = 0; np < 2; ++np) {
;               const int pc = n0 + wn * 64 + np * 32;
;               const int i = ((pc & 255) >> 5) * 16 + l15;
;               const float2 cs = rope[pi * 128 + i];
;               const float x1 = acc[mf][2 * np][r], x2 = acc[mf][2 * np + 1][r];
;               float y1 = x1 * cs.x - x2 * cs.y, y2 = x1 * cs.y + x2 * cs.x;
;               if (pc >= 1024) { y1 *= 0.0625f; y2 *= 0.0625f; }
;               const int f1 = (pc & ~255) + i;
;               proj[f1] = f2bf(y1);
;               proj[f1 + 128] = f2bf(y2);
;             }
;           } else {
; #pragma unroll
;             for (int nf = 0; nf < 4; ++nf) proj[n0 + wn * 64 + nf * 16 + l15] = f2bf(acc[mf][nf][r]);
;           }
;         } else if (EPI == 1) {
; #pragma unroll
;           for (int nf = 0; nf < 4; ++nf) {
;             const int col = n0 + wn * 64 + nf * 16 + l15;
;             const float a = (NH > 0) ? accT[mf][nf][r] : acc[mf][nf][r];
;             outf[(size_t)row * 1024 + col] = rvv[r][nf] + a;
.Lq3_205:
	v_add_u32_e32 v220, 12, v128
	ds_read_b32 v221, v220
	ds_read_b32 v223, v220 offset:256
	ds_read_b32 v225, v220 offset:512
	ds_read_b32 v227, v220 offset:768
	ds_read_b32 v229, v220 offset:2048
	ds_read_b32 v231, v220 offset:2304
	ds_read_b32 v233, v220 offset:2560
	ds_read_b32 v235, v220 offset:2816
	s_waitcnt lgkmcnt(0)
	s_nop 7
	v_mul_f32_e32 v120, v221, v120
	v_mul_f32_e32 v121, v221, v121
	v_mul_f32_e32 v122, v221, v122
	v_mul_f32_e32 v123, v221, v123
	v_mul_f32_e32 v124, v221, v124
	v_mul_f32_e32 v125, v221, v125
	v_mul_f32_e32 v126, v221, v126
	v_mul_f32_e32 v127, v221, v127
	v_mul_f32_e32 v112, v221, v112
	v_mul_f32_e32 v113, v221, v113
	v_mul_f32_e32 v114, v221, v114
	v_mul_f32_e32 v115, v221, v115
	v_mul_f32_e32 v116, v221, v116
	v_mul_f32_e32 v117, v221, v117
	v_mul_f32_e32 v118, v221, v118
	v_mul_f32_e32 v119, v221, v119
	v_mul_f32_e32 v104, v223, v104
	v_mul_f32_e32 v105, v223, v105
	v_mul_f32_e32 v106, v223, v106
	v_mul_f32_e32 v107, v223, v107
	v_mul_f32_e32 v108, v223, v108
	v_mul_f32_e32 v109, v223, v109
	v_mul_f32_e32 v110, v223, v110
	v_mul_f32_e32 v111, v223, v111
	v_mul_f32_e32 v96, v223, v96
	v_mul_f32_e32 v97, v223, v97
	v_mul_f32_e32 v98, v223, v98
	v_mul_f32_e32 v99, v223, v99
	v_mul_f32_e32 v100, v223, v100
	v_mul_f32_e32 v101, v223, v101
	v_mul_f32_e32 v102, v223, v102
	v_mul_f32_e32 v103, v223, v103
	v_mul_f32_e32 v88, v225, v88
	v_mul_f32_e32 v89, v225, v89
	v_mul_f32_e32 v90, v225, v90
	v_mul_f32_e32 v91, v225, v91
	v_mul_f32_e32 v92, v225, v92
	v_mul_f32_e32 v93, v225, v93
	v_mul_f32_e32 v94, v225, v94
	v_mul_f32_e32 v95, v225, v95
	v_mul_f32_e32 v80, v225, v80
	v_mul_f32_e32 v81, v225, v81
	v_mul_f32_e32 v82, v225, v82
	v_mul_f32_e32 v83, v225, v83
	v_mul_f32_e32 v84, v225, v84
	v_mul_f32_e32 v85, v225, v85
	v_mul_f32_e32 v86, v225, v86
	v_mul_f32_e32 v87, v225, v87
	v_mul_f32_e32 v72, v227, v72
	v_mul_f32_e32 v73, v227, v73
	v_mul_f32_e32 v74, v227, v74
	v_mul_f32_e32 v75, v227, v75
	v_mul_f32_e32 v76, v227, v76
	v_mul_f32_e32 v77, v227, v77
	v_mul_f32_e32 v78, v227, v78
	v_mul_f32_e32 v79, v227, v79
	v_mul_f32_e32 v64, v227, v64
	v_mul_f32_e32 v65, v227, v65
	v_mul_f32_e32 v66, v227, v66
	v_mul_f32_e32 v67, v227, v67
	v_mul_f32_e32 v68, v227, v68
	v_mul_f32_e32 v69, v227, v69
	v_mul_f32_e32 v70, v227, v70
	v_mul_f32_e32 v71, v227, v71
	v_mul_f32_e32 v56, v229, v56
	v_mul_f32_e32 v57, v229, v57
	v_mul_f32_e32 v58, v229, v58
	v_mul_f32_e32 v59, v229, v59
	v_mul_f32_e32 v60, v229, v60
	v_mul_f32_e32 v61, v229, v61
	v_mul_f32_e32 v62, v229, v62
	v_mul_f32_e32 v63, v229, v63
	v_mul_f32_e32 v48, v229, v48
	v_mul_f32_e32 v49, v229, v49
	v_mul_f32_e32 v50, v229, v50
	v_mul_f32_e32 v51, v229, v51
	v_mul_f32_e32 v52, v229, v52
	v_mul_f32_e32 v53, v229, v53
	v_mul_f32_e32 v54, v229, v54
	v_mul_f32_e32 v55, v229, v55
	v_mul_f32_e32 v40, v231, v40
	v_mul_f32_e32 v41, v231, v41
	v_mul_f32_e32 v42, v231, v42
	v_mul_f32_e32 v43, v231, v43
	v_mul_f32_e32 v44, v231, v44
	v_mul_f32_e32 v45, v231, v45
	v_mul_f32_e32 v46, v231, v46
	v_mul_f32_e32 v47, v231, v47
	v_mul_f32_e32 v32, v231, v32
	v_mul_f32_e32 v33, v231, v33
	v_mul_f32_e32 v34, v231, v34
	v_mul_f32_e32 v35, v231, v35
	v_mul_f32_e32 v36, v231, v36
	v_mul_f32_e32 v37, v231, v37
	v_mul_f32_e32 v38, v231, v38
	v_mul_f32_e32 v39, v231, v39
	v_mul_f32_e32 v24, v233, v24
	v_mul_f32_e32 v25, v233, v25
	v_mul_f32_e32 v26, v233, v26
	v_mul_f32_e32 v27, v233, v27
	v_mul_f32_e32 v28, v233, v28
	v_mul_f32_e32 v29, v233, v29
	v_mul_f32_e32 v30, v233, v30
	v_mul_f32_e32 v31, v233, v31
	v_mul_f32_e32 v16, v233, v16
	v_mul_f32_e32 v17, v233, v17
	v_mul_f32_e32 v18, v233, v18
	v_mul_f32_e32 v19, v233, v19
	v_mul_f32_e32 v20, v233, v20
	v_mul_f32_e32 v21, v233, v21
	v_mul_f32_e32 v22, v233, v22
	v_mul_f32_e32 v23, v233, v23
	v_mul_f32_e32 v8, v235, v8
	v_mul_f32_e32 v9, v235, v9
	v_mul_f32_e32 v10, v235, v10
	v_mul_f32_e32 v11, v235, v11
	v_mul_f32_e32 v12, v235, v12
	v_mul_f32_e32 v13, v235, v13
	v_mul_f32_e32 v14, v235, v14
	v_mul_f32_e32 v15, v235, v15
	v_mul_f32_e32 v0, v235, v0
	v_mul_f32_e32 v1, v235, v1
	v_mul_f32_e32 v2, v235, v2
	v_mul_f32_e32 v3, v235, v3
	v_mul_f32_e32 v4, v235, v4
	v_mul_f32_e32 v5, v235, v5
	v_mul_f32_e32 v6, v235, v6
	v_mul_f32_e32 v7, v235, v7
	s_barrier
	v_readlane_b32 s4, v255, 51
	v_readlane_b32 s1, v255, 52
	v_readlane_b32 s5, v255, 6
	v_and_b32_e32 v176, 15, v195
	v_lshrrev_b32_e32 v177, 4, v195
	s_lshr_b32 s6, s5, 2
	s_and_b32 s7, s5, 3
	s_lshl_b32 s6, s6, 6
	v_add_u32_e32 v178, s6, v176
	v_mul_u32_u24_e32 v178, 0x410, v178
	s_lshl_b32 s7, s7, 7
	v_lshl_add_u32 v178, v177, 4, v178
	v_add_u32_e32 v178, s7, v178
	s_lshl_b32 s7, s5, 4
	v_lshlrev_b32_e32 v179, 4, v195
	s_mul_i32 s6, s7, 0x410
	v_add_u32_e32 v180, s6, v179
	s_lshl_b32 s4, s4, 8
	s_add_i32 s4, s4, s7
	s_lshl_b32 s4, s4, 12
	s_lshl_b32 s1, s1, 10
	s_add_i32 s4, s4, s1
	v_add_u32_e32 v181, s4, v179
	v_readlane_b32 s0, v255, 0
	v_readlane_b32 s1, v255, 1
	s_load_dwordx2 s[20:21], s[0:1], 0x0
	s_add_u32 s24, s84, 0x15aa2000
	s_addc_u32 s25, s85, 0
	s_waitcnt lgkmcnt(0)
	v_mov_b32_e32 v182, v181
	global_load_dwordx4 v[184:187], v182, s[20:21]
	v_add_u32_e32 v182, 0x1000, v182
	global_load_dwordx4 v[188:191], v182, s[20:21]
	v_add_u32_e32 v182, 0x1000, v182
	global_load_dwordx4 v[196:199], v182, s[20:21]
	v_add_u32_e32 v182, 0x1000, v182
	global_load_dwordx4 v[200:203], v182, s[20:21]
	v_add_u32_e32 v182, 0x1000, v182
	global_load_dwordx4 v[204:207], v182, s[20:21]
	v_add_u32_e32 v182, 0x1000, v182
	global_load_dwordx4 v[208:211], v182, s[20:21]
	v_add_u32_e32 v182, 0x1000, v182
	global_load_dwordx4 v[212:215], v182, s[20:21]
	v_add_u32_e32 v182, 0x1000, v182
	global_load_dwordx4 v[216:219], v182, s[20:21]
	v_add_u32_e32 v182, 0x1000, v182
	global_load_dwordx4 v[220:223], v182, s[20:21]
	v_add_u32_e32 v182, 0x1000, v182
	global_load_dwordx4 v[224:227], v182, s[20:21]
	v_add_u32_e32 v182, 0x1000, v182
	global_load_dwordx4 v[228:231], v182, s[20:21]
	v_add_u32_e32 v182, 0x1000, v182
	global_load_dwordx4 v[232:235], v182, s[20:21]
	v_add_u32_e32 v182, 0x1000, v182
	global_load_dwordx4 v[236:239], v182, s[20:21]
	v_add_u32_e32 v182, 0x1000, v182
	global_load_dwordx4 v[240:243], v182, s[20:21]
	v_add_u32_e32 v182, 0x1000, v182
	global_load_dwordx4 v[244:247], v182, s[20:21]
	v_add_u32_e32 v182, 0x1000, v182
	global_load_dwordx4 v[248:251], v182, s[20:21]
	ds_write_b128 v178, v[120:123]
	ds_write_b128 v178, v[124:127] offset:64
	ds_write_b128 v178, v[104:107] offset:16640
	ds_write_b128 v178, v[108:111] offset:16704
	ds_write_b128 v178, v[88:91] offset:33280
	ds_write_b128 v178, v[92:95] offset:33344
	ds_write_b128 v178, v[72:75] offset:49920
	ds_write_b128 v178, v[76:79] offset:49984
	ds_write_b128 v178, v[112:115] offset:512
	ds_write_b128 v178, v[116:119] offset:576
	ds_write_b128 v178, v[96:99] offset:17152
	ds_write_b128 v178, v[100:103] offset:17216
	ds_write_b128 v178, v[80:83] offset:33792
	ds_write_b128 v178, v[84:87] offset:33856
	ds_write_b128 v178, v[64:67] offset:50432
	ds_write_b128 v178, v[68:71] offset:50496
	s_waitcnt lgkmcnt(0)
	s_barrier
;     ...
;       if (EPI == 1) {
; #pragma unroll
;         for (int r = 0; r < 4; ++r) {
;           const int row = m0 + wm * 64 + mf * 16 + 4 * g + r;
; #pragma unroll
;           for (int nf = 0; nf < 4; ++nf) {
;             const int col = n0 + wn * 64 + nf * 16 + l15;
;             rvv[r][nf] = resid ? resid[(size_t)row * 1024 + col] : xrow(p, row)[col];
;           }
;         }
;       }
; #pragma unroll
;       for (int r = 0; r < 4; ++r) {
;         const int row = m0 + wm * 64 + mf * 16 + 4 * g + r;
;         if (EPI == 0) {
;           u16* proj = (u16*)(p.ws + OFF_PROJ) + (size_t)row * PROJ_LD;
;           if (n0 < 2048) {
;             const float2* rope = (const float2*)(p.ws + OFF_ROPE);
;             const int pi = row < NPROMPT ? (row & 2047) : 2048 + ((row - NPROMPT) & 7);
; #pragma unroll
;             for (int np = 0; np < 2; ++np) {
;               const int pc = n0 + wn * 64 + np * 32;
;               const int i = ((pc & 255) >> 5) * 16 + l15;
;               const float2 cs = rope[pi * 128 + i];
;               const float x1 = acc[mf][2 * np][r], x2 = acc[mf][2 * np + 1][r];
;               float y1 = x1 * cs.x - x2 * cs.y, y2 = x1 * cs.y + x2 * cs.x;
;               if (pc >= 1024) { y1 *= 0.0625f; y2 *= 0.0625f; }
;               const int f1 = (pc & ~255) + i;
;               proj[f1] = f2bf(y1);
;               proj[f1 + 128] = f2bf(y2);
;             }
;           } else {
; #pragma unroll
;             for (int nf = 0; nf < 4; ++nf) proj[n0 + wn * 64 + nf * 16 + l15] = f2bf(acc[mf][nf][r]);
;           }
;         } else if (EPI == 1) {
; #pragma unroll
;           for (int nf = 0; nf < 4; ++nf) {
;             const int col = n0 + wn * 64 + nf * 16 + l15;
;             const float a = (NH > 0) ? accT[mf][nf][r] : acc[mf][nf][r];
;             outf[(size_t)row * 1024 + col] = rvv[r][nf] + a;
;           }
	ds_read_b128 v[64:67], v180
	ds_read_b128 v[68:71], v180 offset:1040
	ds_read_b128 v[72:75], v180 offset:2080
	ds_read_b128 v[76:79], v180 offset:3120
	ds_read_b128 v[80:83], v180 offset:4160
	ds_read_b128 v[84:87], v180 offset:5200
	ds_read_b128 v[88:91], v180 offset:6240
	ds_read_b128 v[92:95], v180 offset:7280
	ds_read_b128 v[96:99], v180 offset:8320
	ds_read_b128 v[100:103], v180 offset:9360
	ds_read_b128 v[104:107], v180 offset:10400
	ds_read_b128 v[108:111], v180 offset:11440
	ds_read_b128 v[112:115], v180 offset:12480
	ds_read_b128 v[116:119], v180 offset:13520
	ds_read_b128 v[120:123], v180 offset:14560
	ds_read_b128 v[124:127], v180 offset:15600
	s_waitcnt lgkmcnt(0)
	s_barrier
	v_mov_b32_e32 v182, v181
	s_waitcnt vmcnt(15)
	v_add_f32_e32 v64, v64, v184
	v_add_f32_e32 v65, v65, v185
	v_add_f32_e32 v66, v66, v186
	v_add_f32_e32 v67, v67, v187
	global_store_dwordx4 v182, v[64:67], s[24:25]
	v_add_u32_e32 v182, 0x1000, v182
	s_waitcnt vmcnt(15)
	v_add_f32_e32 v68, v68, v188
	v_add_f32_e32 v69, v69, v189
	v_add_f32_e32 v70, v70, v190
	v_add_f32_e32 v71, v71, v191
	global_store_dwordx4 v182, v[68:71], s[24:25]
	v_add_u32_e32 v182, 0x1000, v182
	s_waitcnt vmcnt(15)
	v_add_f32_e32 v72, v72, v196
	v_add_f32_e32 v73, v73, v197
	v_add_f32_e32 v74, v74, v198
	v_add_f32_e32 v75, v75, v199
	global_store_dwordx4 v182, v[72:75], s[24:25]
	v_add_u32_e32 v182, 0x1000, v182
	s_waitcnt vmcnt(15)
	v_add_f32_e32 v76, v76, v200
	v_add_f32_e32 v77, v77, v201
	v_add_f32_e32 v78, v78, v202
	v_add_f32_e32 v79, v79, v203
	global_store_dwordx4 v182, v[76:79], s[24:25]
	v_add_u32_e32 v182, 0x1000, v182
	s_waitcnt vmcnt(15)
	v_add_f32_e32 v80, v80, v204
	v_add_f32_e32 v81, v81, v205
	v_add_f32_e32 v82, v82, v206
	v_add_f32_e32 v83, v83, v207
	global_store_dwordx4 v182, v[80:83], s[24:25]
	v_add_u32_e32 v182, 0x1000, v182
	s_waitcnt vmcnt(15)
	v_add_f32_e32 v84, v84, v208
	v_add_f32_e32 v85, v85, v209
	v_add_f32_e32 v86, v86, v210
	v_add_f32_e32 v87, v87, v211
	global_store_dwordx4 v182, v[84:87], s[24:25]
	v_add_u32_e32 v182, 0x1000, v182
	s_waitcnt vmcnt(15)
	v_add_f32_e32 v88, v88, v212
	v_add_f32_e32 v89, v89, v213
	v_add_f32_e32 v90, v90, v214
	v_add_f32_e32 v91, v91, v215
	global_store_dwordx4 v182, v[88:91], s[24:25]
	v_add_u32_e32 v182, 0x1000, v182
	s_waitcnt vmcnt(15)
	v_add_f32_e32 v92, v92, v216
	v_add_f32_e32 v93, v93, v217
	v_add_f32_e32 v94, v94, v218
	v_add_f32_e32 v95, v95, v219
	global_store_dwordx4 v182, v[92:95], s[24:25]
	v_add_u32_e32 v182, 0x1000, v182
	s_waitcnt vmcnt(15)
	v_add_f32_e32 v96, v96, v220
	v_add_f32_e32 v97, v97, v221
	v_add_f32_e32 v98, v98, v222
	v_add_f32_e32 v99, v99, v223
	global_store_dwordx4 v182, v[96:99], s[24:25]
	v_add_u32_e32 v182, 0x1000, v182
	s_waitcnt vmcnt(15)
	v_add_f32_e32 v100, v100, v224
	v_add_f32_e32 v101, v101, v225
	v_add_f32_e32 v102, v102, v226
	v_add_f32_e32 v103, v103, v227
	global_store_dwordx4 v182, v[100:103], s[24:25]
	v_add_u32_e32 v182, 0x1000, v182
	s_waitcnt vmcnt(15)
	v_add_f32_e32 v104, v104, v228
	v_add_f32_e32 v105, v105, v229
	v_add_f32_e32 v106, v106, v230
	v_add_f32_e32 v107, v107, v231
	global_store_dwordx4 v182, v[104:107], s[24:25]
	v_add_u32_e32 v182, 0x1000, v182
	s_waitcnt vmcnt(15)
	v_add_f32_e32 v108, v108, v232
	v_add_f32_e32 v109, v109, v233
	v_add_f32_e32 v110, v110, v234
	v_add_f32_e32 v111, v111, v235
	global_store_dwordx4 v182, v[108:111], s[24:25]
	v_add_u32_e32 v182, 0x1000, v182
	s_waitcnt vmcnt(15)
	v_add_f32_e32 v112, v112, v236
	v_add_f32_e32 v113, v113, v237
	v_add_f32_e32 v114, v114, v238
	v_add_f32_e32 v115, v115, v239
	global_store_dwordx4 v182, v[112:115], s[24:25]
	v_add_u32_e32 v182, 0x1000, v182
	s_waitcnt vmcnt(15)
	v_add_f32_e32 v116, v116, v240
	v_add_f32_e32 v117, v117, v241
	v_add_f32_e32 v118, v118, v242
	v_add_f32_e32 v119, v119, v243
	global_store_dwordx4 v182, v[116:119], s[24:25]
	v_add_u32_e32 v182, 0x1000, v182
	s_waitcnt vmcnt(15)
	v_add_f32_e32 v120, v120, v244
	v_add_f32_e32 v121, v121, v245
	v_add_f32_e32 v122, v122, v246
	v_add_f32_e32 v123, v123, v247
	global_store_dwordx4 v182, v[120:123], s[24:25]
	v_add_u32_e32 v182, 0x1000, v182
	s_waitcnt vmcnt(15)
	v_add_f32_e32 v124, v124, v248
	v_add_f32_e32 v125, v125, v249
	v_add_f32_e32 v126, v126, v250
	v_add_f32_e32 v127, v127, v251
	global_store_dwordx4 v182, v[124:127], s[24:25]
	v_add_u32_e32 v181, 0x80000, v181
	v_mov_b32_e32 v182, v181
	global_load_dwordx4 v[184:187], v182, s[20:21]
	v_add_u32_e32 v182, 0x1000, v182
	global_load_dwordx4 v[188:191], v182, s[20:21]
	v_add_u32_e32 v182, 0x1000, v182
	global_load_dwordx4 v[196:199], v182, s[20:21]
	v_add_u32_e32 v182, 0x1000, v182
	global_load_dwordx4 v[200:203], v182, s[20:21]
	v_add_u32_e32 v182, 0x1000, v182
	global_load_dwordx4 v[204:207], v182, s[20:21]
	v_add_u32_e32 v182, 0x1000, v182
	global_load_dwordx4 v[208:211], v182, s[20:21]
	v_add_u32_e32 v182, 0x1000, v182
	global_load_dwordx4 v[212:215], v182, s[20:21]
	v_add_u32_e32 v182, 0x1000, v182
	global_load_dwordx4 v[216:219], v182, s[20:21]
	v_add_u32_e32 v182, 0x1000, v182
	global_load_dwordx4 v[220:223], v182, s[20:21]
	v_add_u32_e32 v182, 0x1000, v182
	global_load_dwordx4 v[224:227], v182, s[20:21]
	v_add_u32_e32 v182, 0x1000, v182
	global_load_dwordx4 v[228:231], v182, s[20:21]
	v_add_u32_e32 v182, 0x1000, v182
	global_load_dwordx4 v[232:235], v182, s[20:21]
	v_add_u32_e32 v182, 0x1000, v182
	global_load_dwordx4 v[236:239], v182, s[20:21]
	v_add_u32_e32 v182, 0x1000, v182
	global_load_dwordx4 v[240:243], v182, s[20:21]
	v_add_u32_e32 v182, 0x1000, v182
	global_load_dwordx4 v[244:247], v182, s[20:21]
	v_add_u32_e32 v182, 0x1000, v182
	global_load_dwordx4 v[248:251], v182, s[20:21]
	ds_write_b128 v178, v[56:59]
	ds_write_b128 v178, v[60:63] offset:64
	ds_write_b128 v178, v[40:43] offset:16640
	ds_write_b128 v178, v[44:47] offset:16704
	ds_write_b128 v178, v[24:27] offset:33280
	ds_write_b128 v178, v[28:31] offset:33344
	ds_write_b128 v178, v[8:11] offset:49920
	ds_write_b128 v178, v[12:15] offset:49984
	ds_write_b128 v178, v[48:51] offset:512
	ds_write_b128 v178, v[52:55] offset:576
	ds_write_b128 v178, v[32:35] offset:17152
	ds_write_b128 v178, v[36:39] offset:17216
	ds_write_b128 v178, v[16:19] offset:33792
	ds_write_b128 v178, v[20:23] offset:33856
	ds_write_b128 v178, v[0:3] offset:50432
	ds_write_b128 v178, v[4:7] offset:50496
	s_waitcnt lgkmcnt(0)
	s_barrier
;     ...
;   for (int tile0 = rev ? (int)(gridDim.x - 1 - blockIdx.x) : (int)blockIdx.x; tile0 < ntiles * rep; tile0 += gridDim.x) {
;     const int tile = tile0 % ntiles;
;     int mt = tile / NT, nt = tile - mt * NT + nt0;
;     ...
;       if (EPI == 1) {
; #pragma unroll
;         for (int r = 0; r < 4; ++r) {
;           const int row = m0 + wm * 64 + mf * 16 + 4 * g + r;
; #pragma unroll
;           for (int nf = 0; nf < 4; ++nf) {
;             const int col = n0 + wn * 64 + nf * 16 + l15;
;             rvv[r][nf] = resid ? resid[(size_t)row * 1024 + col] : xrow(p, row)[col];
;           }
;         }
;       }
; #pragma unroll
;       for (int r = 0; r < 4; ++r) {
;         const int row = m0 + wm * 64 + mf * 16 + 4 * g + r;
;         if (EPI == 0) {
;           u16* proj = (u16*)(p.ws + OFF_PROJ) + (size_t)row * PROJ_LD;
;           if (n0 < 2048) {
;             const float2* rope = (const float2*)(p.ws + OFF_ROPE);
;             const int pi = row < NPROMPT ? (row & 2047) : 2048 + ((row - NPROMPT) & 7);
; #pragma unroll
;             for (int np = 0; np < 2; ++np) {
;               const int pc = n0 + wn * 64 + np * 32;
;               const int i = ((pc & 255) >> 5) * 16 + l15;
;               const float2 cs = rope[pi * 128 + i];
;               const float x1 = acc[mf][2 * np][r], x2 = acc[mf][2 * np + 1][r];
;               float y1 = x1 * cs.x - x2 * cs.y, y2 = x1 * cs.y + x2 * cs.x;
;               if (pc >= 1024) { y1 *= 0.0625f; y2 *= 0.0625f; }
;               const int f1 = (pc & ~255) + i;
;               proj[f1] = f2bf(y1);
;               proj[f1 + 128] = f2bf(y2);
;             }
;           } else {
; #pragma unroll
;             for (int nf = 0; nf < 4; ++nf) proj[n0 + wn * 64 + nf * 16 + l15] = f2bf(acc[mf][nf][r]);
;           }
;         } else if (EPI == 1) {
; #pragma unroll
;           for (int nf = 0; nf < 4; ++nf) {
;             const int col = n0 + wn * 64 + nf * 16 + l15;
;             const float a = (NH > 0) ? accT[mf][nf][r] : acc[mf][nf][r];
;             outf[(size_t)row * 1024 + col] = rvv[r][nf] + a;
;           }
	ds_read_b128 v[64:67], v180
	ds_read_b128 v[68:71], v180 offset:1040
	ds_read_b128 v[72:75], v180 offset:2080
	ds_read_b128 v[76:79], v180 offset:3120
	ds_read_b128 v[80:83], v180 offset:4160
	ds_read_b128 v[84:87], v180 offset:5200
	ds_read_b128 v[88:91], v180 offset:6240
	ds_read_b128 v[92:95], v180 offset:7280
	ds_read_b128 v[96:99], v180 offset:8320
	ds_read_b128 v[100:103], v180 offset:9360
	ds_read_b128 v[104:107], v180 offset:10400
	ds_read_b128 v[108:111], v180 offset:11440
	ds_read_b128 v[112:115], v180 offset:12480
	ds_read_b128 v[116:119], v180 offset:13520
	ds_read_b128 v[120:123], v180 offset:14560
	ds_read_b128 v[124:127], v180 offset:15600
	s_waitcnt lgkmcnt(0)
	s_barrier
	v_mov_b32_e32 v182, v181
	s_waitcnt vmcnt(15)
	v_add_f32_e32 v64, v64, v184
	v_add_f32_e32 v65, v65, v185
	v_add_f32_e32 v66, v66, v186
	v_add_f32_e32 v67, v67, v187
	global_store_dwordx4 v182, v[64:67], s[24:25]
	v_add_u32_e32 v182, 0x1000, v182
	s_waitcnt vmcnt(15)
	v_add_f32_e32 v68, v68, v188
	v_add_f32_e32 v69, v69, v189
	v_add_f32_e32 v70, v70, v190
	v_add_f32_e32 v71, v71, v191
	global_store_dwordx4 v182, v[68:71], s[24:25]
	v_add_u32_e32 v182, 0x1000, v182
	s_waitcnt vmcnt(15)
	v_add_f32_e32 v72, v72, v196
	v_add_f32_e32 v73, v73, v197
	v_add_f32_e32 v74, v74, v198
	v_add_f32_e32 v75, v75, v199
	global_store_dwordx4 v182, v[72:75], s[24:25]
	v_add_u32_e32 v182, 0x1000, v182
	s_waitcnt vmcnt(15)
	v_add_f32_e32 v76, v76, v200
	v_add_f32_e32 v77, v77, v201
	v_add_f32_e32 v78, v78, v202
	v_add_f32_e32 v79, v79, v203
	global_store_dwordx4 v182, v[76:79], s[24:25]
	v_add_u32_e32 v182, 0x1000, v182
	s_waitcnt vmcnt(15)
	v_add_f32_e32 v80, v80, v204
	v_add_f32_e32 v81, v81, v205
	v_add_f32_e32 v82, v82, v206
	v_add_f32_e32 v83, v83, v207
	global_store_dwordx4 v182, v[80:83], s[24:25]
	v_add_u32_e32 v182, 0x1000, v182
	s_waitcnt vmcnt(15)
	v_add_f32_e32 v84, v84, v208
	v_add_f32_e32 v85, v85, v209
	v_add_f32_e32 v86, v86, v210
	v_add_f32_e32 v87, v87, v211
	global_store_dwordx4 v182, v[84:87], s[24:25]
	v_add_u32_e32 v182, 0x1000, v182
	s_waitcnt vmcnt(15)
	v_add_f32_e32 v88, v88, v212
	v_add_f32_e32 v89, v89, v213
	v_add_f32_e32 v90, v90, v214
	v_add_f32_e32 v91, v91, v215
	global_store_dwordx4 v182, v[88:91], s[24:25]
	v_add_u32_e32 v182, 0x1000, v182
	s_waitcnt vmcnt(15)
	v_add_f32_e32 v92, v92, v216
	v_add_f32_e32 v93, v93, v217
	v_add_f32_e32 v94, v94, v218
	v_add_f32_e32 v95, v95, v219
	global_store_dwordx4 v182, v[92:95], s[24:25]
	v_add_u32_e32 v182, 0x1000, v182
	s_waitcnt vmcnt(15)
	v_add_f32_e32 v96, v96, v220
	v_add_f32_e32 v97, v97, v221
	v_add_f32_e32 v98, v98, v222
	v_add_f32_e32 v99, v99, v223
	global_store_dwordx4 v182, v[96:99], s[24:25]
	v_add_u32_e32 v182, 0x1000, v182
	s_waitcnt vmcnt(15)
	v_add_f32_e32 v100, v100, v224
	v_add_f32_e32 v101, v101, v225
	v_add_f32_e32 v102, v102, v226
	v_add_f32_e32 v103, v103, v227
	global_store_dwordx4 v182, v[100:103], s[24:25]
	v_add_u32_e32 v182, 0x1000, v182
	s_waitcnt vmcnt(15)
	v_add_f32_e32 v104, v104, v228
	v_add_f32_e32 v105, v105, v229
	v_add_f32_e32 v106, v106, v230
	v_add_f32_e32 v107, v107, v231
	global_store_dwordx4 v182, v[104:107], s[24:25]
	v_add_u32_e32 v182, 0x1000, v182
	s_waitcnt vmcnt(15)
	v_add_f32_e32 v108, v108, v232
	v_add_f32_e32 v109, v109, v233
	v_add_f32_e32 v110, v110, v234
	v_add_f32_e32 v111, v111, v235
	global_store_dwordx4 v182, v[108:111], s[24:25]
	v_add_u32_e32 v182, 0x1000, v182
	s_waitcnt vmcnt(15)
	v_add_f32_e32 v112, v112, v236
	v_add_f32_e32 v113, v113, v237
	v_add_f32_e32 v114, v114, v238
	v_add_f32_e32 v115, v115, v239
	global_store_dwordx4 v182, v[112:115], s[24:25]
	v_add_u32_e32 v182, 0x1000, v182
	s_waitcnt vmcnt(15)
	v_add_f32_e32 v116, v116, v240
	v_add_f32_e32 v117, v117, v241
	v_add_f32_e32 v118, v118, v242
	v_add_f32_e32 v119, v119, v243
	global_store_dwordx4 v182, v[116:119], s[24:25]
	v_add_u32_e32 v182, 0x1000, v182
	s_waitcnt vmcnt(15)
	v_add_f32_e32 v120, v120, v244
	v_add_f32_e32 v121, v121, v245
	v_add_f32_e32 v122, v122, v246
	v_add_f32_e32 v123, v123, v247
	global_store_dwordx4 v182, v[120:123], s[24:25]
	v_add_u32_e32 v182, 0x1000, v182
	s_waitcnt vmcnt(15)
	v_add_f32_e32 v124, v124, v248
	v_add_f32_e32 v125, v125, v249
	v_add_f32_e32 v126, v126, v250
	v_add_f32_e32 v127, v127, v251
	global_store_dwordx4 v182, v[124:127], s[24:25]
	s_waitcnt vmcnt(0)
	s_barrier
	v_readlane_b32 s0, v255, 0
	v_readlane_b32 s1, v255, 1
	s_load_dwordx4 s[8:11], s[0:1], 0x0
	s_mov_b64 s[0:1], 0
	s_add_u32 s14, s84, s0
	s_addc_u32 s15, s85, s1
	v_readlane_b32 s23, v255, 6
	s_bfe_u32 s24, s90, 0x10003
	s_lshl_b32 s22, s23, 6
	s_add_i32 s24, s24, 1
	s_add_u32 s6, s14, 0x15aa2000
	s_addc_u32 s7, s15, 0
	s_waitcnt vmcnt(1)
	v_mbcnt_lo_u32_b32 v0, -1, 0
	s_add_u32 s12, s14, 0x15662000
	v_mbcnt_hi_u32_b32 v195, -1, v0
	s_addc_u32 s13, s15, 0
	s_lshl_b32 s25, s24, 9
	s_mov_b32 s25, 0
	s_mov_b64 s[2:3], 0
	v_add_u32_e32 v196, s22, v195
	s_cmp_lt_i32 s78, s25
	v_and_b32_e32 v181, 15, v195
	s_cbranch_scc1 .LBB0_703
	v_and_b32_e32 v0, 15, v195
	s_branch .LBB0_704
